# compress-1 GEMM epilogue: bias vectors loaded once (was 16 load+wait round trips per item)
# baseline (speedup 1.0000x reference)
; DEVI void store_bf4(bf16_t* p, f32x4 v) { u32x2 w; w.x = pk2(v[0], v[1]); w.y = pk2(v[2], v[3]); *(u32x2*)p = w; }
;   DEVI void operator()(int m, int n, f32x4 v, float) const {
;     const float4 bb = *(const float4*)(c1 + n);
;     float x[4] = {v[0] + bb.x, v[1] + bb.y, v[2] + bb.z, v[3] + bb.w};
;     f32x4 o;
; #pragma unroll
;     for (int j = 0; j < 4; ++j) {
;       float y = 0.7978845608028654f * (x[j] + 0.044715f * x[j] * x[j] * x[j]);
;       float th = 1.f - 2.f / (__expf(2.f * y) + 1.f);
;       o[j] = 0.5f * x[j] * (1.f + th);
;     }
;     store_bf4(hid + (size_t)m * 128 + n, o);
;   }
.LBB0_845:
	s_lshl_b32 s92, s4, 7
	s_lshl_b32 s0, s2, 20
	v_readlane_b32 s1, v253, 34
	s_add_u32 s4, s1, s0
	v_readlane_b32 s0, v253, 35
	s_addc_u32 s5, s0, 0
	s_lshl_b64 s[0:1], s[92:93], 2
	v_readlane_b32 s6, v253, 10
	v_readlane_b32 s7, v253, 11
	s_add_u32 s0, s6, s0
	v_lshl_or_b32 v32, v100, 2, v102
	s_addc_u32 s1, s7, s1
	s_waitcnt vmcnt(3)
	v_lshlrev_b32_e32 v70, 2, v32
	global_load_dwordx4 v[182:185], v70, s[0:1]
	global_load_dwordx4 v[186:189], v70, s[0:1] offset:64
	global_load_dwordx4 v[190:193], v70, s[0:1] offset:128
	global_load_dwordx4 v[194:197], v70, s[0:1] offset:192
	v_or_b32_e32 v62, s3, v101
	v_add_u32_e32 v66, v103, v62
	v_lshlrev_b32_e32 v32, 1, v32
	v_lshl_add_u64 v[64:65], s[4:5], 0, v[32:33]
	s_waitcnt vmcnt(0)
	v_mov_b32_e32 v72, v182
	v_mov_b32_e32 v73, v183
	v_mov_b32_e32 v74, v184
	v_mov_b32_e32 v75, v185
	v_add_f32_e32 v62, v86, v72
	v_mul_f32_e32 v68, 0x3d372713, v62
	v_mul_f32_e32 v68, v62, v68
	v_fma_f32 v68, v62, v68, v62
	v_mul_f32_e32 v68, 0x3f4c422a, v68
	v_add_f32_e32 v68, v68, v68
	v_mul_f32_e32 v68, 0x3fb8aa3b, v68
	v_exp_f32_e32 v68, v68
	v_add_f32_e32 v63, v87, v73
	v_add_f32_e32 v67, v88, v74
	v_mul_f32_e32 v62, 0.5, v62
	v_add_f32_e32 v68, 1.0, v68
	v_div_scale_f32 v69, s[2:3], v68, v68, 2.0
	v_rcp_f32_e32 v71, v69
	v_add_f32_e32 v32, v89, v75
	v_fma_f32 v72, -v69, v71, 1.0
	v_fmac_f32_e32 v71, v72, v71
	v_div_scale_f32 v72, vcc, 2.0, v68, 2.0
	v_mul_f32_e32 v73, v72, v71
	v_fma_f32 v74, -v69, v73, v72
	v_fmac_f32_e32 v73, v74, v71
	v_fma_f32 v69, -v69, v73, v72
	v_div_fmas_f32 v69, v69, v71, v73
	v_div_fixup_f32 v68, v69, v68, 2.0
	v_sub_f32_e32 v68, 1.0, v68
	v_add_f32_e32 v68, 1.0, v68
	v_mul_f32_e32 v68, v62, v68
	v_mul_f32_e32 v62, 0x3d372713, v63
	v_mul_f32_e32 v62, v63, v62
	v_fma_f32 v62, v63, v62, v63
	v_mul_f32_e32 v62, 0x3f4c422a, v62
	v_add_f32_e32 v62, v62, v62
	v_mul_f32_e32 v62, 0x3fb8aa3b, v62
	v_exp_f32_e32 v62, v62
	v_mul_f32_e32 v63, 0.5, v63
	v_add_f32_e32 v62, 1.0, v62
	v_div_scale_f32 v69, s[2:3], v62, v62, 2.0
	v_rcp_f32_e32 v71, v69
	s_nop 0
	v_fma_f32 v72, -v69, v71, 1.0
	v_fmac_f32_e32 v71, v72, v71
	v_div_scale_f32 v72, vcc, 2.0, v62, 2.0
	v_mul_f32_e32 v73, v72, v71
	v_fma_f32 v74, -v69, v73, v72
	v_fmac_f32_e32 v73, v74, v71
	v_fma_f32 v69, -v69, v73, v72
	v_div_fmas_f32 v69, v69, v71, v73
	v_div_fixup_f32 v62, v69, v62, 2.0
	v_sub_f32_e32 v62, 1.0, v62
	v_add_f32_e32 v62, 1.0, v62
	v_mul_f32_e32 v69, v63, v62
	v_mul_f32_e32 v62, 0x3d372713, v67
	v_mul_f32_e32 v62, v67, v62
	v_fma_f32 v62, v67, v62, v67
	v_mul_f32_e32 v62, 0x3f4c422a, v62
	v_add_f32_e32 v62, v62, v62
	v_mul_f32_e32 v62, 0x3fb8aa3b, v62
	v_exp_f32_e32 v62, v62
	v_cvt_pk_bf16_f32 v68, v68, v69
	s_nop 0
	v_add_f32_e32 v62, 1.0, v62
	v_div_scale_f32 v63, s[2:3], v62, v62, 2.0
	v_rcp_f32_e32 v71, v63
	s_nop 0
	v_fma_f32 v72, -v63, v71, 1.0
	v_fmac_f32_e32 v71, v72, v71
	v_div_scale_f32 v72, vcc, 2.0, v62, 2.0
	v_mul_f32_e32 v73, v72, v71
	v_fma_f32 v74, -v63, v73, v72
	v_fmac_f32_e32 v73, v74, v71
	v_fma_f32 v63, -v63, v73, v72
	v_div_fmas_f32 v63, v63, v71, v73
	v_div_fixup_f32 v62, v63, v62, 2.0
	v_sub_f32_e32 v62, 1.0, v62
	v_mul_f32_e32 v63, 0.5, v67
	v_add_f32_e32 v62, 1.0, v62
	v_mul_f32_e32 v71, v63, v62
	v_mul_f32_e32 v62, 0x3d372713, v32
	v_mul_f32_e32 v62, v32, v62
	v_fma_f32 v62, v32, v62, v32
	v_mul_f32_e32 v62, 0x3f4c422a, v62
	v_add_f32_e32 v62, v62, v62
	v_mul_f32_e32 v62, 0x3fb8aa3b, v62
	v_exp_f32_e32 v62, v62
	v_mul_f32_e32 v32, 0.5, v32
	v_add_f32_e32 v62, 1.0, v62
	v_div_scale_f32 v63, s[2:3], v62, v62, 2.0
	v_rcp_f32_e32 v67, v63
	s_nop 0
	v_fma_f32 v72, -v63, v67, 1.0
	v_fmac_f32_e32 v67, v72, v67
	v_div_scale_f32 v72, vcc, 2.0, v62, 2.0
	v_mul_f32_e32 v73, v72, v67
	v_fma_f32 v74, -v63, v73, v72
	v_fmac_f32_e32 v73, v74, v67
	v_fma_f32 v63, -v63, v73, v72
	v_div_fmas_f32 v63, v63, v67, v73
	v_div_fixup_f32 v62, v63, v62, 2.0
	v_sub_f32_e32 v62, 1.0, v62
	v_add_f32_e32 v62, 1.0, v62
	v_ashrrev_i32_e32 v67, 31, v66
	v_mul_f32_e32 v32, v32, v62
	v_lshlrev_b64 v[62:63], 8, v[66:67]
	v_lshl_add_u64 v[62:63], v[64:65], 0, v[62:63]
	v_cvt_pk_bf16_f32 v69, v71, v32
	global_store_dwordx2 v[62:63], v[68:69], off
	v_mov_b32_e32 v72, v182
	v_mov_b32_e32 v73, v183
	v_mov_b32_e32 v74, v184
	v_mov_b32_e32 v75, v185
	v_or_b32_e32 v68, 16, v66
	v_add_f32_e32 v58, v58, v72
	v_add_f32_e32 v67, v60, v74
	v_mul_f32_e32 v60, 0x3d372713, v58
	v_mul_f32_e32 v60, v58, v60
	v_fma_f32 v60, v58, v60, v58
	v_mul_f32_e32 v60, 0x3f4c422a, v60
	v_add_f32_e32 v60, v60, v60
	v_mul_f32_e32 v60, 0x3fb8aa3b, v60
	v_exp_f32_e32 v60, v60
	v_add_f32_e32 v32, v61, v75
	v_add_f32_e32 v59, v59, v73
	v_mul_f32_e32 v58, 0.5, v58
	v_add_f32_e32 v60, 1.0, v60
	v_div_scale_f32 v61, s[2:3], v60, v60, 2.0
	v_rcp_f32_e32 v69, v61
	s_nop 0
	v_fma_f32 v71, -v61, v69, 1.0
	v_fmac_f32_e32 v69, v71, v69
	v_div_scale_f32 v71, vcc, 2.0, v60, 2.0
	v_mul_f32_e32 v72, v71, v69
	v_fma_f32 v73, -v61, v72, v71
	v_fmac_f32_e32 v72, v73, v69
	v_fma_f32 v61, -v61, v72, v71
	v_div_fmas_f32 v61, v61, v69, v72
	v_div_fixup_f32 v60, v61, v60, 2.0
	v_sub_f32_e32 v60, 1.0, v60
	v_add_f32_e32 v60, 1.0, v60
	v_mul_f32_e32 v60, v58, v60
	v_mul_f32_e32 v58, 0x3d372713, v59
	v_mul_f32_e32 v58, v59, v58
	v_fma_f32 v58, v59, v58, v59
	v_mul_f32_e32 v58, 0x3f4c422a, v58
	v_add_f32_e32 v58, v58, v58
	v_mul_f32_e32 v58, 0x3fb8aa3b, v58
	v_exp_f32_e32 v58, v58
	v_mul_f32_e32 v59, 0.5, v59
	v_add_f32_e32 v58, 1.0, v58
	v_div_scale_f32 v61, s[2:3], v58, v58, 2.0
	v_rcp_f32_e32 v69, v61
	s_nop 0
	v_fma_f32 v71, -v61, v69, 1.0
	v_fmac_f32_e32 v69, v71, v69
	v_div_scale_f32 v71, vcc, 2.0, v58, 2.0
	v_mul_f32_e32 v72, v71, v69
	v_fma_f32 v73, -v61, v72, v71
; DEVI void store_bf4(bf16_t* p, f32x4 v) { u32x2 w; w.x = pk2(v[0], v[1]); w.y = pk2(v[2], v[3]); *(u32x2*)p = w; }
;   DEVI void operator()(int m, int n, f32x4 v, float) const {
;     const float4 bb = *(const float4*)(c1 + n);
;     float x[4] = {v[0] + bb.x, v[1] + bb.y, v[2] + bb.z, v[3] + bb.w};
;     f32x4 o;
; #pragma unroll
;     for (int j = 0; j < 4; ++j) {
;       float y = 0.7978845608028654f * (x[j] + 0.044715f * x[j] * x[j] * x[j]);
;       float th = 1.f - 2.f / (__expf(2.f * y) + 1.f);
;       o[j] = 0.5f * x[j] * (1.f + th);
;     }
;     store_bf4(hid + (size_t)m * 128 + n, o);
;   }
	v_fmac_f32_e32 v72, v73, v69
	v_fma_f32 v61, -v61, v72, v71
	v_div_fmas_f32 v61, v61, v69, v72
	v_div_fixup_f32 v58, v61, v58, 2.0
	v_sub_f32_e32 v58, 1.0, v58
	v_add_f32_e32 v58, 1.0, v58
	v_mul_f32_e32 v61, v59, v58
	v_mul_f32_e32 v58, 0x3d372713, v67
	v_mul_f32_e32 v58, v67, v58
	v_fma_f32 v58, v67, v58, v67
	v_mul_f32_e32 v58, 0x3f4c422a, v58
	v_add_f32_e32 v58, v58, v58
	v_mul_f32_e32 v58, 0x3fb8aa3b, v58
	v_exp_f32_e32 v58, v58
	v_cvt_pk_bf16_f32 v60, v60, v61
	s_nop 0
	v_add_f32_e32 v58, 1.0, v58
	v_div_scale_f32 v59, s[2:3], v58, v58, 2.0
	v_rcp_f32_e32 v69, v59
	s_nop 0
	v_fma_f32 v71, -v59, v69, 1.0
	v_fmac_f32_e32 v69, v71, v69
	v_div_scale_f32 v71, vcc, 2.0, v58, 2.0
	v_mul_f32_e32 v72, v71, v69
	v_fma_f32 v73, -v59, v72, v71
	v_fmac_f32_e32 v72, v73, v69
	v_fma_f32 v59, -v59, v72, v71
	v_div_fmas_f32 v59, v59, v69, v72
	v_div_fixup_f32 v58, v59, v58, 2.0
	v_sub_f32_e32 v58, 1.0, v58
	v_mul_f32_e32 v59, 0.5, v67
	v_add_f32_e32 v58, 1.0, v58
	v_mul_f32_e32 v67, v59, v58
	v_mul_f32_e32 v58, 0x3d372713, v32
	v_mul_f32_e32 v58, v32, v58
	v_fma_f32 v58, v32, v58, v32
	v_mul_f32_e32 v58, 0x3f4c422a, v58
	v_add_f32_e32 v58, v58, v58
	v_mul_f32_e32 v58, 0x3fb8aa3b, v58
	v_exp_f32_e32 v58, v58
	v_mul_f32_e32 v32, 0.5, v32
	v_add_f32_e32 v58, 1.0, v58
	v_div_scale_f32 v59, s[2:3], v58, v58, 2.0
	v_rcp_f32_e32 v69, v59
	s_nop 0
	v_fma_f32 v71, -v59, v69, 1.0
	v_fmac_f32_e32 v69, v71, v69
	v_div_scale_f32 v71, vcc, 2.0, v58, 2.0
	v_mul_f32_e32 v72, v71, v69
	v_fma_f32 v73, -v59, v72, v71
	v_fmac_f32_e32 v72, v73, v69
	v_fma_f32 v59, -v59, v72, v71
	v_div_fmas_f32 v59, v59, v69, v72
	v_div_fixup_f32 v58, v59, v58, 2.0
	v_sub_f32_e32 v58, 1.0, v58
	v_add_f32_e32 v58, 1.0, v58
	v_ashrrev_i32_e32 v69, 31, v68
	v_mul_f32_e32 v32, v32, v58
	v_lshlrev_b64 v[58:59], 8, v[68:69]
	v_lshl_add_u64 v[58:59], v[64:65], 0, v[58:59]
	v_cvt_pk_bf16_f32 v61, v67, v32
	global_store_dwordx2 v[58:59], v[60:61], off
	v_mov_b32_e32 v72, v182
	v_mov_b32_e32 v73, v183
	v_mov_b32_e32 v74, v184
	v_mov_b32_e32 v75, v185
	v_or_b32_e32 v60, 32, v66
	v_add_f32_e32 v54, v54, v72
	v_add_f32_e32 v61, v56, v74
	v_mul_f32_e32 v56, 0x3d372713, v54
	v_mul_f32_e32 v56, v54, v56
	v_fma_f32 v56, v54, v56, v54
	v_mul_f32_e32 v56, 0x3f4c422a, v56
	v_add_f32_e32 v56, v56, v56
	v_mul_f32_e32 v56, 0x3fb8aa3b, v56
	v_exp_f32_e32 v56, v56
	v_add_f32_e32 v32, v57, v75
	v_add_f32_e32 v55, v55, v73
	v_mul_f32_e32 v54, 0.5, v54
	v_add_f32_e32 v56, 1.0, v56
	v_div_scale_f32 v57, s[2:3], v56, v56, 2.0
	v_rcp_f32_e32 v67, v57
	s_nop 0
	v_fma_f32 v68, -v57, v67, 1.0
	v_fmac_f32_e32 v67, v68, v67
	v_div_scale_f32 v68, vcc, 2.0, v56, 2.0
	v_mul_f32_e32 v69, v68, v67
	v_fma_f32 v71, -v57, v69, v68
	v_fmac_f32_e32 v69, v71, v67
	v_fma_f32 v57, -v57, v69, v68
	v_div_fmas_f32 v57, v57, v67, v69
	v_div_fixup_f32 v56, v57, v56, 2.0
	v_sub_f32_e32 v56, 1.0, v56
	v_add_f32_e32 v56, 1.0, v56
	v_mul_f32_e32 v56, v54, v56
	v_mul_f32_e32 v54, 0x3d372713, v55
	v_mul_f32_e32 v54, v55, v54
	v_fma_f32 v54, v55, v54, v55
	v_mul_f32_e32 v54, 0x3f4c422a, v54
	v_add_f32_e32 v54, v54, v54
	v_mul_f32_e32 v54, 0x3fb8aa3b, v54
	v_exp_f32_e32 v54, v54
	v_mul_f32_e32 v55, 0.5, v55
	v_add_f32_e32 v54, 1.0, v54
	v_div_scale_f32 v57, s[2:3], v54, v54, 2.0
	v_rcp_f32_e32 v67, v57
	s_nop 0
	v_fma_f32 v68, -v57, v67, 1.0
	v_fmac_f32_e32 v67, v68, v67
	v_div_scale_f32 v68, vcc, 2.0, v54, 2.0
	v_mul_f32_e32 v69, v68, v67
	v_fma_f32 v71, -v57, v69, v68
	v_fmac_f32_e32 v69, v71, v67
	v_fma_f32 v57, -v57, v69, v68
	v_div_fmas_f32 v57, v57, v67, v69
	v_div_fixup_f32 v54, v57, v54, 2.0
	v_sub_f32_e32 v54, 1.0, v54
	v_add_f32_e32 v54, 1.0, v54
	v_mul_f32_e32 v57, v55, v54
	v_mul_f32_e32 v54, 0x3d372713, v61
	v_mul_f32_e32 v54, v61, v54
	v_fma_f32 v54, v61, v54, v61
	v_mul_f32_e32 v54, 0x3f4c422a, v54
	v_add_f32_e32 v54, v54, v54
	v_mul_f32_e32 v54, 0x3fb8aa3b, v54
	v_exp_f32_e32 v54, v54
	v_cvt_pk_bf16_f32 v56, v56, v57
	s_nop 0
	v_add_f32_e32 v54, 1.0, v54
	v_div_scale_f32 v55, s[2:3], v54, v54, 2.0
	v_rcp_f32_e32 v67, v55
	s_nop 0
	v_fma_f32 v68, -v55, v67, 1.0
	v_fmac_f32_e32 v67, v68, v67
	v_div_scale_f32 v68, vcc, 2.0, v54, 2.0
	v_mul_f32_e32 v69, v68, v67
	v_fma_f32 v71, -v55, v69, v68
	v_fmac_f32_e32 v69, v71, v67
	v_fma_f32 v55, -v55, v69, v68
	v_div_fmas_f32 v55, v55, v67, v69
	v_div_fixup_f32 v54, v55, v54, 2.0
	v_sub_f32_e32 v54, 1.0, v54
	v_mul_f32_e32 v55, 0.5, v61
	v_add_f32_e32 v54, 1.0, v54
	v_mul_f32_e32 v67, v55, v54
	v_mul_f32_e32 v54, 0x3d372713, v32
	v_mul_f32_e32 v54, v32, v54
	v_fma_f32 v54, v32, v54, v32
	v_mul_f32_e32 v54, 0x3f4c422a, v54
	v_add_f32_e32 v54, v54, v54
	v_mul_f32_e32 v54, 0x3fb8aa3b, v54
	v_exp_f32_e32 v54, v54
	v_mul_f32_e32 v32, 0.5, v32
	v_add_f32_e32 v54, 1.0, v54
	v_div_scale_f32 v55, s[2:3], v54, v54, 2.0
	v_rcp_f32_e32 v61, v55
	s_nop 0
	v_fma_f32 v68, -v55, v61, 1.0
	v_fmac_f32_e32 v61, v68, v61
	v_div_scale_f32 v68, vcc, 2.0, v54, 2.0
	v_mul_f32_e32 v69, v68, v61
	v_fma_f32 v71, -v55, v69, v68
	v_fmac_f32_e32 v69, v71, v61
	v_fma_f32 v55, -v55, v69, v68
	v_div_fmas_f32 v55, v55, v61, v69
	v_div_fixup_f32 v54, v55, v54, 2.0
	v_sub_f32_e32 v54, 1.0, v54
	v_add_f32_e32 v54, 1.0, v54
	v_ashrrev_i32_e32 v61, 31, v60
	v_mul_f32_e32 v32, v32, v54
	v_lshlrev_b64 v[54:55], 8, v[60:61]
	v_lshl_add_u64 v[54:55], v[64:65], 0, v[54:55]
	v_cvt_pk_bf16_f32 v57, v67, v32
	global_store_dwordx2 v[54:55], v[56:57], off
	v_or_b32_e32 v56, 48, v66
	v_mov_b32_e32 v66, v182
	v_mov_b32_e32 v67, v183
	v_mov_b32_e32 v68, v184
	v_mov_b32_e32 v69, v185
	v_add_f32_e32 v50, v50, v66
	v_add_f32_e32 v57, v52, v68
	v_mul_f32_e32 v52, 0x3d372713, v50
	v_mul_f32_e32 v52, v50, v52
	v_fma_f32 v52, v50, v52, v50
; DEVI void store_bf4(bf16_t* p, f32x4 v) { u32x2 w; w.x = pk2(v[0], v[1]); w.y = pk2(v[2], v[3]); *(u32x2*)p = w; }
;   DEVI void operator()(int m, int n, f32x4 v, float) const {
;     const float4 bb = *(const float4*)(c1 + n);
;     float x[4] = {v[0] + bb.x, v[1] + bb.y, v[2] + bb.z, v[3] + bb.w};
;     f32x4 o;
; #pragma unroll
;     for (int j = 0; j < 4; ++j) {
;       float y = 0.7978845608028654f * (x[j] + 0.044715f * x[j] * x[j] * x[j]);
;       float th = 1.f - 2.f / (__expf(2.f * y) + 1.f);
;       o[j] = 0.5f * x[j] * (1.f + th);
;     }
;     store_bf4(hid + (size_t)m * 128 + n, o);
;   }
	v_mul_f32_e32 v52, 0x3f4c422a, v52
	v_add_f32_e32 v52, v52, v52
	v_mul_f32_e32 v52, 0x3fb8aa3b, v52
	v_exp_f32_e32 v52, v52
	v_add_f32_e32 v32, v53, v69
	v_add_f32_e32 v51, v51, v67
	v_mul_f32_e32 v50, 0.5, v50
	v_add_f32_e32 v52, 1.0, v52
	v_div_scale_f32 v53, s[2:3], v52, v52, 2.0
	v_rcp_f32_e32 v60, v53
	s_nop 0
	v_fma_f32 v61, -v53, v60, 1.0
	v_fmac_f32_e32 v60, v61, v60
	v_div_scale_f32 v61, vcc, 2.0, v52, 2.0
	v_mul_f32_e32 v66, v61, v60
	v_fma_f32 v67, -v53, v66, v61
	v_fmac_f32_e32 v66, v67, v60
	v_fma_f32 v53, -v53, v66, v61
	v_div_fmas_f32 v53, v53, v60, v66
	v_div_fixup_f32 v52, v53, v52, 2.0
	v_sub_f32_e32 v52, 1.0, v52
	v_add_f32_e32 v52, 1.0, v52
	v_mul_f32_e32 v52, v50, v52
	v_mul_f32_e32 v50, 0x3d372713, v51
	v_mul_f32_e32 v50, v51, v50
	v_fma_f32 v50, v51, v50, v51
	v_mul_f32_e32 v50, 0x3f4c422a, v50
	v_add_f32_e32 v50, v50, v50
	v_mul_f32_e32 v50, 0x3fb8aa3b, v50
	v_exp_f32_e32 v50, v50
	v_mul_f32_e32 v51, 0.5, v51
	v_add_f32_e32 v50, 1.0, v50
	v_div_scale_f32 v53, s[2:3], v50, v50, 2.0
	v_rcp_f32_e32 v60, v53
	s_nop 0
	v_fma_f32 v61, -v53, v60, 1.0
	v_fmac_f32_e32 v60, v61, v60
	v_div_scale_f32 v61, vcc, 2.0, v50, 2.0
	v_mul_f32_e32 v66, v61, v60
	v_fma_f32 v67, -v53, v66, v61
	v_fmac_f32_e32 v66, v67, v60
	v_fma_f32 v53, -v53, v66, v61
	v_div_fmas_f32 v53, v53, v60, v66
	v_div_fixup_f32 v50, v53, v50, 2.0
	v_sub_f32_e32 v50, 1.0, v50
	v_add_f32_e32 v50, 1.0, v50
	v_mul_f32_e32 v53, v51, v50
	v_mul_f32_e32 v50, 0x3d372713, v57
	v_mul_f32_e32 v50, v57, v50
	v_fma_f32 v50, v57, v50, v57
	v_mul_f32_e32 v50, 0x3f4c422a, v50
	v_add_f32_e32 v50, v50, v50
	v_mul_f32_e32 v50, 0x3fb8aa3b, v50
	v_exp_f32_e32 v50, v50
	v_cvt_pk_bf16_f32 v52, v52, v53
	s_nop 0
	v_add_f32_e32 v50, 1.0, v50
	v_div_scale_f32 v51, s[2:3], v50, v50, 2.0
	v_rcp_f32_e32 v60, v51
	s_nop 0
	v_fma_f32 v61, -v51, v60, 1.0
	v_fmac_f32_e32 v60, v61, v60
	v_div_scale_f32 v61, vcc, 2.0, v50, 2.0
	v_mul_f32_e32 v66, v61, v60
	v_fma_f32 v67, -v51, v66, v61
	v_fmac_f32_e32 v66, v67, v60
	v_fma_f32 v51, -v51, v66, v61
	v_div_fmas_f32 v51, v51, v60, v66
	v_div_fixup_f32 v50, v51, v50, 2.0
	v_sub_f32_e32 v50, 1.0, v50
	v_mul_f32_e32 v51, 0.5, v57
	v_add_f32_e32 v50, 1.0, v50
	v_mul_f32_e32 v60, v51, v50
	v_mul_f32_e32 v50, 0x3d372713, v32
	v_mul_f32_e32 v50, v32, v50
	v_fma_f32 v50, v32, v50, v32
	v_mul_f32_e32 v50, 0x3f4c422a, v50
	v_add_f32_e32 v50, v50, v50
	v_mul_f32_e32 v50, 0x3fb8aa3b, v50
	v_exp_f32_e32 v50, v50
	v_mul_f32_e32 v32, 0.5, v32
	v_add_f32_e32 v50, 1.0, v50
	v_div_scale_f32 v51, s[2:3], v50, v50, 2.0
	v_rcp_f32_e32 v57, v51
	s_nop 0
	v_fma_f32 v61, -v51, v57, 1.0
	v_fmac_f32_e32 v57, v61, v57
	v_div_scale_f32 v61, vcc, 2.0, v50, 2.0
	v_mul_f32_e32 v66, v61, v57
	v_fma_f32 v67, -v51, v66, v61
	v_fmac_f32_e32 v66, v67, v57
	v_fma_f32 v51, -v51, v66, v61
	v_div_fmas_f32 v51, v51, v57, v66
	v_div_fixup_f32 v50, v51, v50, 2.0
	v_sub_f32_e32 v50, 1.0, v50
	v_add_f32_e32 v50, 1.0, v50
	v_ashrrev_i32_e32 v57, 31, v56
	v_mul_f32_e32 v32, v32, v50
	v_lshlrev_b64 v[50:51], 8, v[56:57]
	v_lshl_add_u64 v[50:51], v[64:65], 0, v[50:51]
	v_cvt_pk_bf16_f32 v53, v60, v32
	global_store_dwordx2 v[50:51], v[52:53], off
	v_mov_b32_e32 v64, v186
	v_mov_b32_e32 v65, v187
	v_mov_b32_e32 v66, v188
	v_mov_b32_e32 v67, v189
	v_add_f32_e32 v46, v46, v64
	v_add_f32_e32 v32, v49, v67
	v_mul_f32_e32 v49, 0x3d372713, v46
	v_mul_f32_e32 v49, v46, v49
	v_fma_f32 v49, v46, v49, v46
	v_mul_f32_e32 v49, 0x3f4c422a, v49
	v_add_f32_e32 v49, v49, v49
	v_mul_f32_e32 v49, 0x3fb8aa3b, v49
	v_exp_f32_e32 v49, v49
	v_add_f32_e32 v47, v47, v65
	v_mul_f32_e32 v46, 0.5, v46
	v_add_f32_e32 v48, v48, v66
	v_add_f32_e32 v49, 1.0, v49
	v_div_scale_f32 v52, s[2:3], v49, v49, 2.0
	v_rcp_f32_e32 v53, v52
	s_nop 0
	v_fma_f32 v56, -v52, v53, 1.0
	v_fmac_f32_e32 v53, v56, v53
	v_div_scale_f32 v56, vcc, 2.0, v49, 2.0
	v_mul_f32_e32 v57, v56, v53
	v_fma_f32 v60, -v52, v57, v56
	v_fmac_f32_e32 v57, v60, v53
	v_fma_f32 v52, -v52, v57, v56
	v_div_fmas_f32 v52, v52, v53, v57
	v_div_fixup_f32 v49, v52, v49, 2.0
	v_sub_f32_e32 v49, 1.0, v49
	v_add_f32_e32 v49, 1.0, v49
	v_mul_f32_e32 v46, v46, v49
	v_mul_f32_e32 v49, 0x3d372713, v47
	v_mul_f32_e32 v49, v47, v49
	v_fma_f32 v49, v47, v49, v47
	v_mul_f32_e32 v49, 0x3f4c422a, v49
	v_add_f32_e32 v49, v49, v49
	v_mul_f32_e32 v49, 0x3fb8aa3b, v49
	v_exp_f32_e32 v49, v49
	v_mul_f32_e32 v47, 0.5, v47
	v_add_f32_e32 v49, 1.0, v49
	v_div_scale_f32 v52, s[2:3], v49, v49, 2.0
	v_rcp_f32_e32 v53, v52
	s_nop 0
	v_fma_f32 v56, -v52, v53, 1.0
	v_fmac_f32_e32 v53, v56, v53
	v_div_scale_f32 v56, vcc, 2.0, v49, 2.0
	v_mul_f32_e32 v57, v56, v53
	v_fma_f32 v60, -v52, v57, v56
	v_fmac_f32_e32 v57, v60, v53
	v_fma_f32 v52, -v52, v57, v56
	v_div_fmas_f32 v52, v52, v53, v57
	v_div_fixup_f32 v49, v52, v49, 2.0
	v_sub_f32_e32 v49, 1.0, v49
	v_add_f32_e32 v49, 1.0, v49
	v_mul_f32_e32 v47, v47, v49
	v_mul_f32_e32 v49, 0x3d372713, v48
	v_mul_f32_e32 v49, v48, v49
	v_fma_f32 v49, v48, v49, v48
	v_mul_f32_e32 v49, 0x3f4c422a, v49
	v_add_f32_e32 v49, v49, v49
	v_mul_f32_e32 v49, 0x3fb8aa3b, v49
	v_exp_f32_e32 v49, v49
	v_mul_f32_e32 v48, 0.5, v48
	v_cvt_pk_bf16_f32 v46, v46, v47
	v_add_f32_e32 v49, 1.0, v49
	v_div_scale_f32 v52, s[2:3], v49, v49, 2.0
	v_rcp_f32_e32 v53, v52
	s_nop 0
	v_fma_f32 v56, -v52, v53, 1.0
	v_fmac_f32_e32 v53, v56, v53
	v_div_scale_f32 v56, vcc, 2.0, v49, 2.0
	v_mul_f32_e32 v57, v56, v53
	v_fma_f32 v60, -v52, v57, v56
	v_fmac_f32_e32 v57, v60, v53
	v_fma_f32 v52, -v52, v57, v56
	v_div_fmas_f32 v52, v52, v53, v57
	v_div_fixup_f32 v49, v52, v49, 2.0
	v_sub_f32_e32 v49, 1.0, v49
	v_add_f32_e32 v49, 1.0, v49
	v_mul_f32_e32 v48, v48, v49
	v_mul_f32_e32 v49, 0x3d372713, v32
; DEVI void store_bf4(bf16_t* p, f32x4 v) { u32x2 w; w.x = pk2(v[0], v[1]); w.y = pk2(v[2], v[3]); *(u32x2*)p = w; }
;   DEVI void operator()(int m, int n, f32x4 v, float) const {
;     const float4 bb = *(const float4*)(c1 + n);
;     float x[4] = {v[0] + bb.x, v[1] + bb.y, v[2] + bb.z, v[3] + bb.w};
;     f32x4 o;
; #pragma unroll
;     for (int j = 0; j < 4; ++j) {
;       float y = 0.7978845608028654f * (x[j] + 0.044715f * x[j] * x[j] * x[j]);
;       float th = 1.f - 2.f / (__expf(2.f * y) + 1.f);
;       o[j] = 0.5f * x[j] * (1.f + th);
;     }
;     store_bf4(hid + (size_t)m * 128 + n, o);
;   }
	v_mul_f32_e32 v49, v32, v49
	v_fma_f32 v49, v32, v49, v32
	v_mul_f32_e32 v49, 0x3f4c422a, v49
	v_add_f32_e32 v49, v49, v49
	v_mul_f32_e32 v49, 0x3fb8aa3b, v49
	v_exp_f32_e32 v49, v49
	v_mul_f32_e32 v32, 0.5, v32
	v_add_f32_e32 v49, 1.0, v49
	v_div_scale_f32 v52, s[2:3], v49, v49, 2.0
	v_rcp_f32_e32 v53, v52
	s_nop 0
	v_fma_f32 v56, -v52, v53, 1.0
	v_fmac_f32_e32 v53, v56, v53
	v_div_scale_f32 v56, vcc, 2.0, v49, 2.0
	v_mul_f32_e32 v57, v56, v53
	v_fma_f32 v60, -v52, v57, v56
	v_fmac_f32_e32 v57, v60, v53
	v_fma_f32 v52, -v52, v57, v56
	v_div_fmas_f32 v52, v52, v53, v57
	v_div_fixup_f32 v49, v52, v49, 2.0
	v_sub_f32_e32 v49, 1.0, v49
	v_add_f32_e32 v49, 1.0, v49
	v_mul_f32_e32 v32, v32, v49
	v_cvt_pk_bf16_f32 v47, v48, v32
	global_store_dwordx2 v[62:63], v[46:47], off offset:32
	v_mov_b32_e32 v46, v186
	v_mov_b32_e32 v47, v187
	v_mov_b32_e32 v48, v188
	v_mov_b32_e32 v49, v189
	v_add_f32_e32 v42, v42, v46
	v_add_f32_e32 v32, v45, v49
	v_mul_f32_e32 v45, 0x3d372713, v42
	v_mul_f32_e32 v45, v42, v45
	v_fma_f32 v45, v42, v45, v42
	v_mul_f32_e32 v45, 0x3f4c422a, v45
	v_add_f32_e32 v45, v45, v45
	v_mul_f32_e32 v45, 0x3fb8aa3b, v45
	v_exp_f32_e32 v45, v45
	v_add_f32_e32 v43, v43, v47
	v_add_f32_e32 v44, v44, v48
	v_mul_f32_e32 v42, 0.5, v42
	v_add_f32_e32 v45, 1.0, v45
	v_div_scale_f32 v46, s[2:3], v45, v45, 2.0
	v_rcp_f32_e32 v47, v46
	s_nop 0
	v_fma_f32 v48, -v46, v47, 1.0
	v_fmac_f32_e32 v47, v48, v47
	v_div_scale_f32 v48, vcc, 2.0, v45, 2.0
	v_mul_f32_e32 v49, v48, v47
	v_fma_f32 v52, -v46, v49, v48
	v_fmac_f32_e32 v49, v52, v47
	v_fma_f32 v46, -v46, v49, v48
	v_div_fmas_f32 v46, v46, v47, v49
	v_div_fixup_f32 v45, v46, v45, 2.0
	v_sub_f32_e32 v45, 1.0, v45
	v_add_f32_e32 v45, 1.0, v45
	v_mul_f32_e32 v42, v42, v45
	v_mul_f32_e32 v45, 0x3d372713, v43
	v_mul_f32_e32 v45, v43, v45
	v_fma_f32 v45, v43, v45, v43
	v_mul_f32_e32 v45, 0x3f4c422a, v45
	v_add_f32_e32 v45, v45, v45
	v_mul_f32_e32 v45, 0x3fb8aa3b, v45
	v_exp_f32_e32 v45, v45
	v_mul_f32_e32 v43, 0.5, v43
	v_add_f32_e32 v45, 1.0, v45
	v_div_scale_f32 v46, s[2:3], v45, v45, 2.0
	v_rcp_f32_e32 v47, v46
	s_nop 0
	v_fma_f32 v48, -v46, v47, 1.0
	v_fmac_f32_e32 v47, v48, v47
	v_div_scale_f32 v48, vcc, 2.0, v45, 2.0
	v_mul_f32_e32 v49, v48, v47
	v_fma_f32 v52, -v46, v49, v48
	v_fmac_f32_e32 v49, v52, v47
	v_fma_f32 v46, -v46, v49, v48
	v_div_fmas_f32 v46, v46, v47, v49
	v_div_fixup_f32 v45, v46, v45, 2.0
	v_sub_f32_e32 v45, 1.0, v45
	v_add_f32_e32 v45, 1.0, v45
	v_mul_f32_e32 v43, v43, v45
	v_mul_f32_e32 v45, 0x3d372713, v44
	v_mul_f32_e32 v45, v44, v45
	v_fma_f32 v45, v44, v45, v44
	v_mul_f32_e32 v45, 0x3f4c422a, v45
	v_add_f32_e32 v45, v45, v45
	v_mul_f32_e32 v45, 0x3fb8aa3b, v45
	v_exp_f32_e32 v45, v45
	v_mul_f32_e32 v44, 0.5, v44
	v_cvt_pk_bf16_f32 v42, v42, v43
	v_add_f32_e32 v45, 1.0, v45
	v_div_scale_f32 v46, s[2:3], v45, v45, 2.0
	v_rcp_f32_e32 v47, v46
	s_nop 0
	v_fma_f32 v48, -v46, v47, 1.0
	v_fmac_f32_e32 v47, v48, v47
	v_div_scale_f32 v48, vcc, 2.0, v45, 2.0
	v_mul_f32_e32 v49, v48, v47
	v_fma_f32 v52, -v46, v49, v48
	v_fmac_f32_e32 v49, v52, v47
	v_fma_f32 v46, -v46, v49, v48
	v_div_fmas_f32 v46, v46, v47, v49
	v_div_fixup_f32 v45, v46, v45, 2.0
	v_sub_f32_e32 v45, 1.0, v45
	v_add_f32_e32 v45, 1.0, v45
	v_mul_f32_e32 v44, v44, v45
	v_mul_f32_e32 v45, 0x3d372713, v32
	v_mul_f32_e32 v45, v32, v45
	v_fma_f32 v45, v32, v45, v32
	v_mul_f32_e32 v45, 0x3f4c422a, v45
	v_add_f32_e32 v45, v45, v45
	v_mul_f32_e32 v45, 0x3fb8aa3b, v45
	v_exp_f32_e32 v45, v45
	v_mul_f32_e32 v32, 0.5, v32
	v_add_f32_e32 v45, 1.0, v45
	v_div_scale_f32 v46, s[2:3], v45, v45, 2.0
	v_rcp_f32_e32 v47, v46
	s_nop 0
	v_fma_f32 v48, -v46, v47, 1.0
	v_fmac_f32_e32 v47, v48, v47
	v_div_scale_f32 v48, vcc, 2.0, v45, 2.0
	v_mul_f32_e32 v49, v48, v47
	v_fma_f32 v52, -v46, v49, v48
	v_fmac_f32_e32 v49, v52, v47
	v_fma_f32 v46, -v46, v49, v48
	v_div_fmas_f32 v46, v46, v47, v49
	v_div_fixup_f32 v45, v46, v45, 2.0
	v_sub_f32_e32 v45, 1.0, v45
	v_add_f32_e32 v45, 1.0, v45
	v_mul_f32_e32 v32, v32, v45
	v_cvt_pk_bf16_f32 v43, v44, v32
	global_store_dwordx2 v[58:59], v[42:43], off offset:32
	v_mov_b32_e32 v42, v186
	v_mov_b32_e32 v43, v187
	v_mov_b32_e32 v44, v188
	v_mov_b32_e32 v45, v189
	v_add_f32_e32 v38, v38, v42
	v_add_f32_e32 v32, v41, v45
	v_mul_f32_e32 v41, 0x3d372713, v38
	v_mul_f32_e32 v41, v38, v41
	v_fma_f32 v41, v38, v41, v38
	v_mul_f32_e32 v41, 0x3f4c422a, v41
	v_add_f32_e32 v41, v41, v41
	v_mul_f32_e32 v41, 0x3fb8aa3b, v41
	v_exp_f32_e32 v41, v41
	v_add_f32_e32 v39, v39, v43
	v_add_f32_e32 v40, v40, v44
	v_mul_f32_e32 v38, 0.5, v38
	v_add_f32_e32 v41, 1.0, v41
	v_div_scale_f32 v42, s[2:3], v41, v41, 2.0
	v_rcp_f32_e32 v43, v42
	s_nop 0
	v_fma_f32 v44, -v42, v43, 1.0
	v_fmac_f32_e32 v43, v44, v43
	v_div_scale_f32 v44, vcc, 2.0, v41, 2.0
	v_mul_f32_e32 v45, v44, v43
	v_fma_f32 v46, -v42, v45, v44
	v_fmac_f32_e32 v45, v46, v43
	v_fma_f32 v42, -v42, v45, v44
	v_div_fmas_f32 v42, v42, v43, v45
	v_div_fixup_f32 v41, v42, v41, 2.0
	v_sub_f32_e32 v41, 1.0, v41
	v_add_f32_e32 v41, 1.0, v41
	v_mul_f32_e32 v38, v38, v41
	v_mul_f32_e32 v41, 0x3d372713, v39
	v_mul_f32_e32 v41, v39, v41
	v_fma_f32 v41, v39, v41, v39
	v_mul_f32_e32 v41, 0x3f4c422a, v41
	v_add_f32_e32 v41, v41, v41
	v_mul_f32_e32 v41, 0x3fb8aa3b, v41
	v_exp_f32_e32 v41, v41
	v_mul_f32_e32 v39, 0.5, v39
	v_add_f32_e32 v41, 1.0, v41
	v_div_scale_f32 v42, s[2:3], v41, v41, 2.0
	v_rcp_f32_e32 v43, v42
	s_nop 0
	v_fma_f32 v44, -v42, v43, 1.0
	v_fmac_f32_e32 v43, v44, v43
	v_div_scale_f32 v44, vcc, 2.0, v41, 2.0
	v_mul_f32_e32 v45, v44, v43
	v_fma_f32 v46, -v42, v45, v44
	v_fmac_f32_e32 v45, v46, v43
	v_fma_f32 v42, -v42, v45, v44
	v_div_fmas_f32 v42, v42, v43, v45
; DEVI void store_bf4(bf16_t* p, f32x4 v) { u32x2 w; w.x = pk2(v[0], v[1]); w.y = pk2(v[2], v[3]); *(u32x2*)p = w; }
;   DEVI void operator()(int m, int n, f32x4 v, float) const {
;     const float4 bb = *(const float4*)(c1 + n);
;     float x[4] = {v[0] + bb.x, v[1] + bb.y, v[2] + bb.z, v[3] + bb.w};
;     f32x4 o;
; #pragma unroll
;     for (int j = 0; j < 4; ++j) {
;       float y = 0.7978845608028654f * (x[j] + 0.044715f * x[j] * x[j] * x[j]);
;       float th = 1.f - 2.f / (__expf(2.f * y) + 1.f);
;       o[j] = 0.5f * x[j] * (1.f + th);
;     }
;     store_bf4(hid + (size_t)m * 128 + n, o);
;   }
	v_div_fixup_f32 v41, v42, v41, 2.0
	v_sub_f32_e32 v41, 1.0, v41
	v_add_f32_e32 v41, 1.0, v41
	v_mul_f32_e32 v39, v39, v41
	v_mul_f32_e32 v41, 0x3d372713, v40
	v_mul_f32_e32 v41, v40, v41
	v_fma_f32 v41, v40, v41, v40
	v_mul_f32_e32 v41, 0x3f4c422a, v41
	v_add_f32_e32 v41, v41, v41
	v_mul_f32_e32 v41, 0x3fb8aa3b, v41
	v_exp_f32_e32 v41, v41
	v_mul_f32_e32 v40, 0.5, v40
	v_cvt_pk_bf16_f32 v38, v38, v39
	v_add_f32_e32 v41, 1.0, v41
	v_div_scale_f32 v42, s[2:3], v41, v41, 2.0
	v_rcp_f32_e32 v43, v42
	s_nop 0
	v_fma_f32 v44, -v42, v43, 1.0
	v_fmac_f32_e32 v43, v44, v43
	v_div_scale_f32 v44, vcc, 2.0, v41, 2.0
	v_mul_f32_e32 v45, v44, v43
	v_fma_f32 v46, -v42, v45, v44
	v_fmac_f32_e32 v45, v46, v43
	v_fma_f32 v42, -v42, v45, v44
	v_div_fmas_f32 v42, v42, v43, v45
	v_div_fixup_f32 v41, v42, v41, 2.0
	v_sub_f32_e32 v41, 1.0, v41
	v_add_f32_e32 v41, 1.0, v41
	v_mul_f32_e32 v40, v40, v41
	v_mul_f32_e32 v41, 0x3d372713, v32
	v_mul_f32_e32 v41, v32, v41
	v_fma_f32 v41, v32, v41, v32
	v_mul_f32_e32 v41, 0x3f4c422a, v41
	v_add_f32_e32 v41, v41, v41
	v_mul_f32_e32 v41, 0x3fb8aa3b, v41
	v_exp_f32_e32 v41, v41
	v_mul_f32_e32 v32, 0.5, v32
	v_add_f32_e32 v41, 1.0, v41
	v_div_scale_f32 v42, s[2:3], v41, v41, 2.0
	v_rcp_f32_e32 v43, v42
	s_nop 0
	v_fma_f32 v44, -v42, v43, 1.0
	v_fmac_f32_e32 v43, v44, v43
	v_div_scale_f32 v44, vcc, 2.0, v41, 2.0
	v_mul_f32_e32 v45, v44, v43
	v_fma_f32 v46, -v42, v45, v44
	v_fmac_f32_e32 v45, v46, v43
	v_fma_f32 v42, -v42, v45, v44
	v_div_fmas_f32 v42, v42, v43, v45
	v_div_fixup_f32 v41, v42, v41, 2.0
	v_sub_f32_e32 v41, 1.0, v41
	v_add_f32_e32 v41, 1.0, v41
	v_mul_f32_e32 v32, v32, v41
	v_cvt_pk_bf16_f32 v39, v40, v32
	global_store_dwordx2 v[54:55], v[38:39], off offset:32
	v_mov_b32_e32 v38, v186
	v_mov_b32_e32 v39, v187
	v_mov_b32_e32 v40, v188
	v_mov_b32_e32 v41, v189
	v_add_f32_e32 v34, v34, v38
	v_add_f32_e32 v32, v37, v41
	v_mul_f32_e32 v37, 0x3d372713, v34
	v_mul_f32_e32 v37, v34, v37
	v_fma_f32 v37, v34, v37, v34
	v_mul_f32_e32 v37, 0x3f4c422a, v37
	v_add_f32_e32 v37, v37, v37
	v_mul_f32_e32 v37, 0x3fb8aa3b, v37
	v_exp_f32_e32 v37, v37
	v_add_f32_e32 v35, v35, v39
	v_add_f32_e32 v36, v36, v40
	v_mul_f32_e32 v34, 0.5, v34
	v_add_f32_e32 v37, 1.0, v37
	v_div_scale_f32 v38, s[2:3], v37, v37, 2.0
	v_rcp_f32_e32 v39, v38
	s_nop 0
	v_fma_f32 v40, -v38, v39, 1.0
	v_fmac_f32_e32 v39, v40, v39
	v_div_scale_f32 v40, vcc, 2.0, v37, 2.0
	v_mul_f32_e32 v41, v40, v39
	v_fma_f32 v42, -v38, v41, v40
	v_fmac_f32_e32 v41, v42, v39
	v_fma_f32 v38, -v38, v41, v40
	v_div_fmas_f32 v38, v38, v39, v41
	v_div_fixup_f32 v37, v38, v37, 2.0
	v_sub_f32_e32 v37, 1.0, v37
	v_add_f32_e32 v37, 1.0, v37
	v_mul_f32_e32 v34, v34, v37
	v_mul_f32_e32 v37, 0x3d372713, v35
	v_mul_f32_e32 v37, v35, v37
	v_fma_f32 v37, v35, v37, v35
	v_mul_f32_e32 v37, 0x3f4c422a, v37
	v_add_f32_e32 v37, v37, v37
	v_mul_f32_e32 v37, 0x3fb8aa3b, v37
	v_exp_f32_e32 v37, v37
	v_mul_f32_e32 v35, 0.5, v35
	v_add_f32_e32 v37, 1.0, v37
	v_div_scale_f32 v38, s[2:3], v37, v37, 2.0
	v_rcp_f32_e32 v39, v38
	s_nop 0
	v_fma_f32 v40, -v38, v39, 1.0
	v_fmac_f32_e32 v39, v40, v39
	v_div_scale_f32 v40, vcc, 2.0, v37, 2.0
	v_mul_f32_e32 v41, v40, v39
	v_fma_f32 v42, -v38, v41, v40
	v_fmac_f32_e32 v41, v42, v39
	v_fma_f32 v38, -v38, v41, v40
	v_div_fmas_f32 v38, v38, v39, v41
	v_div_fixup_f32 v37, v38, v37, 2.0
	v_sub_f32_e32 v37, 1.0, v37
	v_add_f32_e32 v37, 1.0, v37
	v_mul_f32_e32 v35, v35, v37
	v_mul_f32_e32 v37, 0x3d372713, v36
	v_mul_f32_e32 v37, v36, v37
	v_fma_f32 v37, v36, v37, v36
	v_mul_f32_e32 v37, 0x3f4c422a, v37
	v_add_f32_e32 v37, v37, v37
	v_mul_f32_e32 v37, 0x3fb8aa3b, v37
	v_exp_f32_e32 v37, v37
	v_mul_f32_e32 v36, 0.5, v36
	v_cvt_pk_bf16_f32 v34, v34, v35
	v_add_f32_e32 v37, 1.0, v37
	v_div_scale_f32 v38, s[2:3], v37, v37, 2.0
	v_rcp_f32_e32 v39, v38
	s_nop 0
	v_fma_f32 v40, -v38, v39, 1.0
	v_fmac_f32_e32 v39, v40, v39
	v_div_scale_f32 v40, vcc, 2.0, v37, 2.0
	v_mul_f32_e32 v41, v40, v39
	v_fma_f32 v42, -v38, v41, v40
	v_fmac_f32_e32 v41, v42, v39
	v_fma_f32 v38, -v38, v41, v40
	v_div_fmas_f32 v38, v38, v39, v41
	v_div_fixup_f32 v37, v38, v37, 2.0
	v_sub_f32_e32 v37, 1.0, v37
	v_add_f32_e32 v37, 1.0, v37
	v_mul_f32_e32 v36, v36, v37
	v_mul_f32_e32 v37, 0x3d372713, v32
	v_mul_f32_e32 v37, v32, v37
	v_fma_f32 v37, v32, v37, v32
	v_mul_f32_e32 v37, 0x3f4c422a, v37
	v_add_f32_e32 v37, v37, v37
	v_mul_f32_e32 v37, 0x3fb8aa3b, v37
	v_exp_f32_e32 v37, v37
	v_mul_f32_e32 v32, 0.5, v32
	v_add_f32_e32 v37, 1.0, v37
	v_div_scale_f32 v38, s[2:3], v37, v37, 2.0
	v_rcp_f32_e32 v39, v38
	s_nop 0
	v_fma_f32 v40, -v38, v39, 1.0
	v_fmac_f32_e32 v39, v40, v39
	v_div_scale_f32 v40, vcc, 2.0, v37, 2.0
	v_mul_f32_e32 v41, v40, v39
	v_fma_f32 v42, -v38, v41, v40
	v_fmac_f32_e32 v41, v42, v39
	v_fma_f32 v38, -v38, v41, v40
	v_div_fmas_f32 v38, v38, v39, v41
	v_div_fixup_f32 v37, v38, v37, 2.0
	v_sub_f32_e32 v37, 1.0, v37
	v_add_f32_e32 v37, 1.0, v37
	v_mul_f32_e32 v32, v32, v37
	v_cvt_pk_bf16_f32 v35, v36, v32
	global_store_dwordx2 v[50:51], v[34:35], off offset:32
	v_mov_b32_e32 v34, v190
	v_mov_b32_e32 v35, v191
	v_mov_b32_e32 v36, v192
	v_mov_b32_e32 v37, v193
	v_add_f32_e32 v32, v28, v34
	v_add_f32_e32 v34, v29, v35
	v_mul_f32_e32 v29, 0x3d372713, v32
	v_mul_f32_e32 v29, v32, v29
	v_fma_f32 v29, v32, v29, v32
	v_mul_f32_e32 v29, 0x3f4c422a, v29
	v_add_f32_e32 v29, v29, v29
	v_mul_f32_e32 v29, 0x3fb8aa3b, v29
	v_exp_f32_e32 v29, v29
	v_add_f32_e32 v28, v31, v37
	v_add_f32_e32 v30, v30, v36
	v_add_f32_e32 v29, 1.0, v29
	v_div_scale_f32 v31, s[2:3], v29, v29, 2.0
	v_rcp_f32_e32 v35, v31
	s_nop 0
	v_fma_f32 v36, -v31, v35, 1.0
	v_fmac_f32_e32 v35, v36, v35
	v_div_scale_f32 v36, vcc, 2.0, v29, 2.0
; DEVI void store_bf4(bf16_t* p, f32x4 v) { u32x2 w; w.x = pk2(v[0], v[1]); w.y = pk2(v[2], v[3]); *(u32x2*)p = w; }
;   DEVI void operator()(int m, int n, f32x4 v, float) const {
;     const float4 bb = *(const float4*)(c1 + n);
;     float x[4] = {v[0] + bb.x, v[1] + bb.y, v[2] + bb.z, v[3] + bb.w};
;     f32x4 o;
; #pragma unroll
;     for (int j = 0; j < 4; ++j) {
;       float y = 0.7978845608028654f * (x[j] + 0.044715f * x[j] * x[j] * x[j]);
;       float th = 1.f - 2.f / (__expf(2.f * y) + 1.f);
;       o[j] = 0.5f * x[j] * (1.f + th);
;     }
;     store_bf4(hid + (size_t)m * 128 + n, o);
;   }
	v_mul_f32_e32 v37, v36, v35
	v_fma_f32 v38, -v31, v37, v36
	v_fmac_f32_e32 v37, v38, v35
	v_fma_f32 v31, -v31, v37, v36
	v_div_fmas_f32 v31, v31, v35, v37
	v_div_fixup_f32 v29, v31, v29, 2.0
	v_sub_f32_e32 v29, 1.0, v29
	v_mul_f32_e32 v31, 0.5, v32
	v_add_f32_e32 v29, 1.0, v29
	v_mul_f32_e32 v29, v31, v29
	v_mul_f32_e32 v31, 0x3d372713, v34
	v_mul_f32_e32 v31, v34, v31
	v_fma_f32 v31, v34, v31, v34
	v_mul_f32_e32 v31, 0x3f4c422a, v31
	v_add_f32_e32 v31, v31, v31
	v_mul_f32_e32 v31, 0x3fb8aa3b, v31
	v_exp_f32_e32 v31, v31
	s_nop 0
	v_add_f32_e32 v31, 1.0, v31
	v_div_scale_f32 v32, s[2:3], v31, v31, 2.0
	v_rcp_f32_e32 v35, v32
	s_nop 0
	v_fma_f32 v36, -v32, v35, 1.0
	v_fmac_f32_e32 v35, v36, v35
	v_div_scale_f32 v36, vcc, 2.0, v31, 2.0
	v_mul_f32_e32 v37, v36, v35
	v_fma_f32 v38, -v32, v37, v36
	v_fmac_f32_e32 v37, v38, v35
	v_fma_f32 v32, -v32, v37, v36
	v_div_fmas_f32 v32, v32, v35, v37
	v_div_fixup_f32 v31, v32, v31, 2.0
	v_sub_f32_e32 v31, 1.0, v31
	v_mul_f32_e32 v32, 0.5, v34
	v_add_f32_e32 v31, 1.0, v31
	v_mul_f32_e32 v31, v32, v31
	v_mul_f32_e32 v32, 0x3d372713, v30
	v_mul_f32_e32 v32, v30, v32
	v_fma_f32 v32, v30, v32, v30
	v_mul_f32_e32 v32, 0x3f4c422a, v32
	v_add_f32_e32 v32, v32, v32
	v_mul_f32_e32 v32, 0x3fb8aa3b, v32
	v_exp_f32_e32 v32, v32
	v_mul_f32_e32 v30, 0.5, v30
	v_add_f32_e32 v32, 1.0, v32
	v_div_scale_f32 v34, s[2:3], v32, v32, 2.0
	v_rcp_f32_e32 v35, v34
	s_nop 0
	v_fma_f32 v36, -v34, v35, 1.0
	v_fmac_f32_e32 v35, v36, v35
	v_div_scale_f32 v36, vcc, 2.0, v32, 2.0
	v_mul_f32_e32 v37, v36, v35
	v_fma_f32 v38, -v34, v37, v36
	v_fmac_f32_e32 v37, v38, v35
	v_fma_f32 v34, -v34, v37, v36
	v_div_fmas_f32 v34, v34, v35, v37
	v_div_fixup_f32 v32, v34, v32, 2.0
	v_sub_f32_e32 v32, 1.0, v32
	v_add_f32_e32 v32, 1.0, v32
	v_mul_f32_e32 v30, v30, v32
	v_mul_f32_e32 v32, 0x3d372713, v28
	v_mul_f32_e32 v32, v28, v32
	v_fma_f32 v32, v28, v32, v28
	v_mul_f32_e32 v32, 0x3f4c422a, v32
	v_add_f32_e32 v32, v32, v32
	v_mul_f32_e32 v32, 0x3fb8aa3b, v32
	v_exp_f32_e32 v32, v32
	v_mul_f32_e32 v28, 0.5, v28
	v_add_f32_e32 v32, 1.0, v32
	v_div_scale_f32 v34, s[2:3], v32, v32, 2.0
	v_rcp_f32_e32 v35, v34
	s_nop 0
	v_fma_f32 v36, -v34, v35, 1.0
	v_fmac_f32_e32 v35, v36, v35
	v_div_scale_f32 v36, vcc, 2.0, v32, 2.0
	v_mul_f32_e32 v37, v36, v35
	v_fma_f32 v38, -v34, v37, v36
	v_fmac_f32_e32 v37, v38, v35
	v_fma_f32 v34, -v34, v37, v36
	v_div_fmas_f32 v34, v34, v35, v37
	v_div_fixup_f32 v32, v34, v32, 2.0
	v_sub_f32_e32 v32, 1.0, v32
	v_add_f32_e32 v32, 1.0, v32
	v_mul_f32_e32 v32, v28, v32
	v_cvt_pk_bf16_f32 v28, v29, v31
	v_cvt_pk_bf16_f32 v29, v30, v32
	global_store_dwordx2 v[62:63], v[28:29], off offset:64
	v_mov_b32_e32 v28, v190
	v_mov_b32_e32 v29, v191
	v_mov_b32_e32 v30, v192
	v_mov_b32_e32 v31, v193
	v_add_f32_e32 v28, v24, v28
	v_add_f32_e32 v29, v25, v29
	v_mul_f32_e32 v25, 0x3d372713, v28
	v_mul_f32_e32 v25, v28, v25
	v_fma_f32 v25, v28, v25, v28
	v_mul_f32_e32 v25, 0x3f4c422a, v25
	v_add_f32_e32 v25, v25, v25
	v_mul_f32_e32 v25, 0x3fb8aa3b, v25
	v_exp_f32_e32 v25, v25
	v_add_f32_e32 v24, v27, v31
	v_add_f32_e32 v26, v26, v30
	v_add_f32_e32 v25, 1.0, v25
	v_div_scale_f32 v27, s[2:3], v25, v25, 2.0
	v_rcp_f32_e32 v30, v27
	s_nop 0
	v_fma_f32 v31, -v27, v30, 1.0
	v_fmac_f32_e32 v30, v31, v30
	v_div_scale_f32 v31, vcc, 2.0, v25, 2.0
	v_mul_f32_e32 v32, v31, v30
	v_fma_f32 v34, -v27, v32, v31
	v_fmac_f32_e32 v32, v34, v30
	v_fma_f32 v27, -v27, v32, v31
	v_div_fmas_f32 v27, v27, v30, v32
	v_div_fixup_f32 v25, v27, v25, 2.0
	v_sub_f32_e32 v25, 1.0, v25
	v_mul_f32_e32 v27, 0.5, v28
	v_add_f32_e32 v25, 1.0, v25
	v_mul_f32_e32 v25, v27, v25
	v_mul_f32_e32 v27, 0x3d372713, v29
	v_mul_f32_e32 v27, v29, v27
	v_fma_f32 v27, v29, v27, v29
	v_mul_f32_e32 v27, 0x3f4c422a, v27
	v_add_f32_e32 v27, v27, v27
	v_mul_f32_e32 v27, 0x3fb8aa3b, v27
	v_exp_f32_e32 v27, v27
	s_nop 0
	v_add_f32_e32 v27, 1.0, v27
	v_div_scale_f32 v28, s[2:3], v27, v27, 2.0
	v_rcp_f32_e32 v30, v28
	s_nop 0
	v_fma_f32 v31, -v28, v30, 1.0
	v_fmac_f32_e32 v30, v31, v30
	v_div_scale_f32 v31, vcc, 2.0, v27, 2.0
	v_mul_f32_e32 v32, v31, v30
	v_fma_f32 v34, -v28, v32, v31
	v_fmac_f32_e32 v32, v34, v30
	v_fma_f32 v28, -v28, v32, v31
	v_div_fmas_f32 v28, v28, v30, v32
	v_div_fixup_f32 v27, v28, v27, 2.0
	v_sub_f32_e32 v27, 1.0, v27
	v_mul_f32_e32 v28, 0.5, v29
	v_add_f32_e32 v27, 1.0, v27
	v_mul_f32_e32 v27, v28, v27
	v_mul_f32_e32 v28, 0x3d372713, v26
	v_mul_f32_e32 v28, v26, v28
	v_fma_f32 v28, v26, v28, v26
	v_mul_f32_e32 v28, 0x3f4c422a, v28
	v_add_f32_e32 v28, v28, v28
	v_mul_f32_e32 v28, 0x3fb8aa3b, v28
	v_exp_f32_e32 v28, v28
	v_mul_f32_e32 v26, 0.5, v26
	v_add_f32_e32 v28, 1.0, v28
	v_div_scale_f32 v29, s[2:3], v28, v28, 2.0
	v_rcp_f32_e32 v30, v29
	s_nop 0
	v_fma_f32 v31, -v29, v30, 1.0
	v_fmac_f32_e32 v30, v31, v30
	v_div_scale_f32 v31, vcc, 2.0, v28, 2.0
	v_mul_f32_e32 v32, v31, v30
	v_fma_f32 v34, -v29, v32, v31
	v_fmac_f32_e32 v32, v34, v30
	v_fma_f32 v29, -v29, v32, v31
	v_div_fmas_f32 v29, v29, v30, v32
	v_div_fixup_f32 v28, v29, v28, 2.0
	v_sub_f32_e32 v28, 1.0, v28
	v_add_f32_e32 v28, 1.0, v28
	v_mul_f32_e32 v26, v26, v28
	v_mul_f32_e32 v28, 0x3d372713, v24
	v_mul_f32_e32 v28, v24, v28
	v_fma_f32 v28, v24, v28, v24
	v_mul_f32_e32 v28, 0x3f4c422a, v28
	v_add_f32_e32 v28, v28, v28
	v_mul_f32_e32 v28, 0x3fb8aa3b, v28
	v_exp_f32_e32 v28, v28
	v_mul_f32_e32 v24, 0.5, v24
	v_add_f32_e32 v28, 1.0, v28
	v_div_scale_f32 v29, s[2:3], v28, v28, 2.0
	v_rcp_f32_e32 v30, v29
	s_nop 0
	v_fma_f32 v31, -v29, v30, 1.0
	v_fmac_f32_e32 v30, v31, v30
	v_div_scale_f32 v31, vcc, 2.0, v28, 2.0
	v_mul_f32_e32 v32, v31, v30
	v_fma_f32 v34, -v29, v32, v31
	v_fmac_f32_e32 v32, v34, v30
; DEVI void store_bf4(bf16_t* p, f32x4 v) { u32x2 w; w.x = pk2(v[0], v[1]); w.y = pk2(v[2], v[3]); *(u32x2*)p = w; }
;   DEVI void operator()(int m, int n, f32x4 v, float) const {
;     const float4 bb = *(const float4*)(c1 + n);
;     float x[4] = {v[0] + bb.x, v[1] + bb.y, v[2] + bb.z, v[3] + bb.w};
;     f32x4 o;
; #pragma unroll
;     for (int j = 0; j < 4; ++j) {
;       float y = 0.7978845608028654f * (x[j] + 0.044715f * x[j] * x[j] * x[j]);
;       float th = 1.f - 2.f / (__expf(2.f * y) + 1.f);
;       o[j] = 0.5f * x[j] * (1.f + th);
;     }
;     store_bf4(hid + (size_t)m * 128 + n, o);
	v_fma_f32 v29, -v29, v32, v31
	v_div_fmas_f32 v29, v29, v30, v32
	v_div_fixup_f32 v28, v29, v28, 2.0
	v_sub_f32_e32 v28, 1.0, v28
	v_add_f32_e32 v28, 1.0, v28
	v_mul_f32_e32 v28, v24, v28
	v_cvt_pk_bf16_f32 v24, v25, v27
	v_cvt_pk_bf16_f32 v25, v26, v28
	global_store_dwordx2 v[58:59], v[24:25], off offset:64
	v_mov_b32_e32 v24, v190
	v_mov_b32_e32 v25, v191
	v_mov_b32_e32 v26, v192
	v_mov_b32_e32 v27, v193
	v_add_f32_e32 v24, v20, v24
	v_add_f32_e32 v25, v21, v25
	v_mul_f32_e32 v21, 0x3d372713, v24
	v_mul_f32_e32 v21, v24, v21
	v_fma_f32 v21, v24, v21, v24
	v_mul_f32_e32 v21, 0x3f4c422a, v21
	v_add_f32_e32 v21, v21, v21
	v_mul_f32_e32 v21, 0x3fb8aa3b, v21
	v_exp_f32_e32 v21, v21
	v_add_f32_e32 v20, v23, v27
	v_add_f32_e32 v22, v22, v26
	v_add_f32_e32 v21, 1.0, v21
	v_div_scale_f32 v23, s[2:3], v21, v21, 2.0
	v_rcp_f32_e32 v26, v23
	s_nop 0
	v_fma_f32 v27, -v23, v26, 1.0
	v_fmac_f32_e32 v26, v27, v26
	v_div_scale_f32 v27, vcc, 2.0, v21, 2.0
	v_mul_f32_e32 v28, v27, v26
	v_fma_f32 v29, -v23, v28, v27
	v_fmac_f32_e32 v28, v29, v26
	v_fma_f32 v23, -v23, v28, v27
	v_div_fmas_f32 v23, v23, v26, v28
	v_div_fixup_f32 v21, v23, v21, 2.0
	v_sub_f32_e32 v21, 1.0, v21
	v_mul_f32_e32 v23, 0.5, v24
	v_add_f32_e32 v21, 1.0, v21
	v_mul_f32_e32 v21, v23, v21
	v_mul_f32_e32 v23, 0x3d372713, v25
	v_mul_f32_e32 v23, v25, v23
	v_fma_f32 v23, v25, v23, v25
	v_mul_f32_e32 v23, 0x3f4c422a, v23
	v_add_f32_e32 v23, v23, v23
	v_mul_f32_e32 v23, 0x3fb8aa3b, v23
	v_exp_f32_e32 v23, v23
	s_nop 0
	v_add_f32_e32 v23, 1.0, v23
	v_div_scale_f32 v24, s[2:3], v23, v23, 2.0
	v_rcp_f32_e32 v26, v24
	s_nop 0
	v_fma_f32 v27, -v24, v26, 1.0
	v_fmac_f32_e32 v26, v27, v26
	v_div_scale_f32 v27, vcc, 2.0, v23, 2.0
	v_mul_f32_e32 v28, v27, v26
	v_fma_f32 v29, -v24, v28, v27
	v_fmac_f32_e32 v28, v29, v26
	v_fma_f32 v24, -v24, v28, v27
	v_div_fmas_f32 v24, v24, v26, v28
	v_div_fixup_f32 v23, v24, v23, 2.0
	v_sub_f32_e32 v23, 1.0, v23
	v_mul_f32_e32 v24, 0.5, v25
	v_add_f32_e32 v23, 1.0, v23
	v_mul_f32_e32 v23, v24, v23
	v_mul_f32_e32 v24, 0x3d372713, v22
	v_mul_f32_e32 v24, v22, v24
	v_fma_f32 v24, v22, v24, v22
	v_mul_f32_e32 v24, 0x3f4c422a, v24
	v_add_f32_e32 v24, v24, v24
	v_mul_f32_e32 v24, 0x3fb8aa3b, v24
	v_exp_f32_e32 v24, v24
	v_mul_f32_e32 v22, 0.5, v22
	v_add_f32_e32 v24, 1.0, v24
	v_div_scale_f32 v25, s[2:3], v24, v24, 2.0
	v_rcp_f32_e32 v26, v25
	s_nop 0
	v_fma_f32 v27, -v25, v26, 1.0
	v_fmac_f32_e32 v26, v27, v26
	v_div_scale_f32 v27, vcc, 2.0, v24, 2.0
	v_mul_f32_e32 v28, v27, v26
	v_fma_f32 v29, -v25, v28, v27
	v_fmac_f32_e32 v28, v29, v26
	v_fma_f32 v25, -v25, v28, v27
	v_div_fmas_f32 v25, v25, v26, v28
	v_div_fixup_f32 v24, v25, v24, 2.0
	v_sub_f32_e32 v24, 1.0, v24
	v_add_f32_e32 v24, 1.0, v24
	v_mul_f32_e32 v22, v22, v24
	v_mul_f32_e32 v24, 0x3d372713, v20
	v_mul_f32_e32 v24, v20, v24
	v_fma_f32 v24, v20, v24, v20
	v_mul_f32_e32 v24, 0x3f4c422a, v24
	v_add_f32_e32 v24, v24, v24
	v_mul_f32_e32 v24, 0x3fb8aa3b, v24
	v_exp_f32_e32 v24, v24
	v_mul_f32_e32 v20, 0.5, v20
	v_add_f32_e32 v24, 1.0, v24
	v_div_scale_f32 v25, s[2:3], v24, v24, 2.0
	v_rcp_f32_e32 v26, v25
	s_nop 0
	v_fma_f32 v27, -v25, v26, 1.0
	v_fmac_f32_e32 v26, v27, v26
	v_div_scale_f32 v27, vcc, 2.0, v24, 2.0
	v_mul_f32_e32 v28, v27, v26
	v_fma_f32 v29, -v25, v28, v27
	v_fmac_f32_e32 v28, v29, v26
	v_fma_f32 v25, -v25, v28, v27
	v_div_fmas_f32 v25, v25, v26, v28
	v_div_fixup_f32 v24, v25, v24, 2.0
	v_sub_f32_e32 v24, 1.0, v24
	v_add_f32_e32 v24, 1.0, v24
	v_mul_f32_e32 v24, v20, v24
	v_cvt_pk_bf16_f32 v20, v21, v23
	v_cvt_pk_bf16_f32 v21, v22, v24
	global_store_dwordx2 v[54:55], v[20:21], off offset:64
	v_mov_b32_e32 v20, v190
	v_mov_b32_e32 v21, v191
	v_mov_b32_e32 v22, v192
	v_mov_b32_e32 v23, v193
	v_add_f32_e32 v20, v16, v20
	v_add_f32_e32 v21, v17, v21
	v_mul_f32_e32 v17, 0x3d372713, v20
	v_mul_f32_e32 v17, v20, v17
	v_fma_f32 v17, v20, v17, v20
	v_mul_f32_e32 v17, 0x3f4c422a, v17
	v_add_f32_e32 v17, v17, v17
	v_mul_f32_e32 v17, 0x3fb8aa3b, v17
	v_exp_f32_e32 v17, v17
	v_add_f32_e32 v16, v19, v23
	v_add_f32_e32 v18, v18, v22
	v_add_f32_e32 v17, 1.0, v17
	v_div_scale_f32 v19, s[2:3], v17, v17, 2.0
	v_rcp_f32_e32 v22, v19
	s_nop 0
	v_fma_f32 v23, -v19, v22, 1.0
	v_fmac_f32_e32 v22, v23, v22
	v_div_scale_f32 v23, vcc, 2.0, v17, 2.0
	v_mul_f32_e32 v24, v23, v22
	v_fma_f32 v25, -v19, v24, v23
	v_fmac_f32_e32 v24, v25, v22
	v_fma_f32 v19, -v19, v24, v23
	v_div_fmas_f32 v19, v19, v22, v24
	v_div_fixup_f32 v17, v19, v17, 2.0
	v_sub_f32_e32 v17, 1.0, v17
	v_mul_f32_e32 v19, 0.5, v20
	v_add_f32_e32 v17, 1.0, v17
	v_mul_f32_e32 v17, v19, v17
	v_mul_f32_e32 v19, 0x3d372713, v21
	v_mul_f32_e32 v19, v21, v19
	v_fma_f32 v19, v21, v19, v21
	v_mul_f32_e32 v19, 0x3f4c422a, v19
	v_add_f32_e32 v19, v19, v19
	v_mul_f32_e32 v19, 0x3fb8aa3b, v19
	v_exp_f32_e32 v19, v19
	s_nop 0
	v_add_f32_e32 v19, 1.0, v19
	v_div_scale_f32 v20, s[2:3], v19, v19, 2.0
	v_rcp_f32_e32 v22, v20
	s_nop 0
	v_fma_f32 v23, -v20, v22, 1.0
	v_fmac_f32_e32 v22, v23, v22
	v_div_scale_f32 v23, vcc, 2.0, v19, 2.0
	v_mul_f32_e32 v24, v23, v22
	v_fma_f32 v25, -v20, v24, v23
	v_fmac_f32_e32 v24, v25, v22
	v_fma_f32 v20, -v20, v24, v23
	v_div_fmas_f32 v20, v20, v22, v24
	v_div_fixup_f32 v19, v20, v19, 2.0
	v_sub_f32_e32 v19, 1.0, v19
	v_mul_f32_e32 v20, 0.5, v21
	v_add_f32_e32 v19, 1.0, v19
	v_mul_f32_e32 v19, v20, v19
	v_mul_f32_e32 v20, 0x3d372713, v18
	v_mul_f32_e32 v20, v18, v20
	v_fma_f32 v20, v18, v20, v18
	v_mul_f32_e32 v20, 0x3f4c422a, v20
	v_add_f32_e32 v20, v20, v20
	v_mul_f32_e32 v20, 0x3fb8aa3b, v20
	v_exp_f32_e32 v20, v20
	v_mul_f32_e32 v18, 0.5, v18
	v_add_f32_e32 v20, 1.0, v20
	v_div_scale_f32 v21, s[2:3], v20, v20, 2.0
	v_rcp_f32_e32 v22, v21
; DEVI void store_bf4(bf16_t* p, f32x4 v) { u32x2 w; w.x = pk2(v[0], v[1]); w.y = pk2(v[2], v[3]); *(u32x2*)p = w; }
;   DEVI void operator()(int m, int n, f32x4 v, float) const {
;     const float4 bb = *(const float4*)(c1 + n);
;     float x[4] = {v[0] + bb.x, v[1] + bb.y, v[2] + bb.z, v[3] + bb.w};
;     f32x4 o;
; #pragma unroll
;     for (int j = 0; j < 4; ++j) {
;       float y = 0.7978845608028654f * (x[j] + 0.044715f * x[j] * x[j] * x[j]);
;       float th = 1.f - 2.f / (__expf(2.f * y) + 1.f);
;       o[j] = 0.5f * x[j] * (1.f + th);
;     }
;     store_bf4(hid + (size_t)m * 128 + n, o);
	s_nop 0
	v_fma_f32 v23, -v21, v22, 1.0
	v_fmac_f32_e32 v22, v23, v22
	v_div_scale_f32 v23, vcc, 2.0, v20, 2.0
	v_mul_f32_e32 v24, v23, v22
	v_fma_f32 v25, -v21, v24, v23
	v_fmac_f32_e32 v24, v25, v22
	v_fma_f32 v21, -v21, v24, v23
	v_div_fmas_f32 v21, v21, v22, v24
	v_div_fixup_f32 v20, v21, v20, 2.0
	v_sub_f32_e32 v20, 1.0, v20
	v_add_f32_e32 v20, 1.0, v20
	v_mul_f32_e32 v18, v18, v20
	v_mul_f32_e32 v20, 0x3d372713, v16
	v_mul_f32_e32 v20, v16, v20
	v_fma_f32 v20, v16, v20, v16
	v_mul_f32_e32 v20, 0x3f4c422a, v20
	v_add_f32_e32 v20, v20, v20
	v_mul_f32_e32 v20, 0x3fb8aa3b, v20
	v_exp_f32_e32 v20, v20
	v_mul_f32_e32 v16, 0.5, v16
	v_add_f32_e32 v20, 1.0, v20
	v_div_scale_f32 v21, s[2:3], v20, v20, 2.0
	v_rcp_f32_e32 v22, v21
	s_nop 0
	v_fma_f32 v23, -v21, v22, 1.0
	v_fmac_f32_e32 v22, v23, v22
	v_div_scale_f32 v23, vcc, 2.0, v20, 2.0
	v_mul_f32_e32 v24, v23, v22
	v_fma_f32 v25, -v21, v24, v23
	v_fmac_f32_e32 v24, v25, v22
	v_fma_f32 v21, -v21, v24, v23
	v_div_fmas_f32 v21, v21, v22, v24
	v_div_fixup_f32 v20, v21, v20, 2.0
	v_sub_f32_e32 v20, 1.0, v20
	v_add_f32_e32 v20, 1.0, v20
	v_mul_f32_e32 v20, v16, v20
	v_cvt_pk_bf16_f32 v16, v17, v19
	v_cvt_pk_bf16_f32 v17, v18, v20
	global_store_dwordx2 v[50:51], v[16:17], off offset:64
	v_mov_b32_e32 v16, v194
	v_mov_b32_e32 v17, v195
	v_mov_b32_e32 v18, v196
	v_mov_b32_e32 v19, v197
	v_add_f32_e32 v16, v12, v16
	v_add_f32_e32 v17, v13, v17
	v_mul_f32_e32 v13, 0x3d372713, v16
	v_mul_f32_e32 v13, v16, v13
	v_fma_f32 v13, v16, v13, v16
	v_mul_f32_e32 v13, 0x3f4c422a, v13
	v_add_f32_e32 v13, v13, v13
	v_mul_f32_e32 v13, 0x3fb8aa3b, v13
	v_exp_f32_e32 v13, v13
	v_add_f32_e32 v12, v15, v19
	v_add_f32_e32 v14, v14, v18
	v_add_f32_e32 v13, 1.0, v13
	v_div_scale_f32 v15, s[2:3], v13, v13, 2.0
	v_rcp_f32_e32 v18, v15
	s_nop 0
	v_fma_f32 v19, -v15, v18, 1.0
	v_fmac_f32_e32 v18, v19, v18
	v_div_scale_f32 v19, vcc, 2.0, v13, 2.0
	v_mul_f32_e32 v20, v19, v18
	v_fma_f32 v21, -v15, v20, v19
	v_fmac_f32_e32 v20, v21, v18
	v_fma_f32 v15, -v15, v20, v19
	v_div_fmas_f32 v15, v15, v18, v20
	v_div_fixup_f32 v13, v15, v13, 2.0
	v_sub_f32_e32 v13, 1.0, v13
	v_mul_f32_e32 v15, 0.5, v16
	v_add_f32_e32 v13, 1.0, v13
	v_mul_f32_e32 v13, v15, v13
	v_mul_f32_e32 v15, 0x3d372713, v17
	v_mul_f32_e32 v15, v17, v15
	v_fma_f32 v15, v17, v15, v17
	v_mul_f32_e32 v15, 0x3f4c422a, v15
	v_add_f32_e32 v15, v15, v15
	v_mul_f32_e32 v15, 0x3fb8aa3b, v15
	v_exp_f32_e32 v15, v15
	s_nop 0
	v_add_f32_e32 v15, 1.0, v15
	v_div_scale_f32 v16, s[2:3], v15, v15, 2.0
	v_rcp_f32_e32 v18, v16
	s_nop 0
	v_fma_f32 v19, -v16, v18, 1.0
	v_fmac_f32_e32 v18, v19, v18
	v_div_scale_f32 v19, vcc, 2.0, v15, 2.0
	v_mul_f32_e32 v20, v19, v18
	v_fma_f32 v21, -v16, v20, v19
	v_fmac_f32_e32 v20, v21, v18
	v_fma_f32 v16, -v16, v20, v19
	v_div_fmas_f32 v16, v16, v18, v20
	v_div_fixup_f32 v15, v16, v15, 2.0
	v_sub_f32_e32 v15, 1.0, v15
	v_mul_f32_e32 v16, 0.5, v17
	v_add_f32_e32 v15, 1.0, v15
	v_mul_f32_e32 v15, v16, v15
	v_mul_f32_e32 v16, 0x3d372713, v14
	v_mul_f32_e32 v16, v14, v16
	v_fma_f32 v16, v14, v16, v14
	v_mul_f32_e32 v16, 0x3f4c422a, v16
	v_add_f32_e32 v16, v16, v16
	v_mul_f32_e32 v16, 0x3fb8aa3b, v16
	v_exp_f32_e32 v16, v16
	v_mul_f32_e32 v14, 0.5, v14
	v_add_f32_e32 v16, 1.0, v16
	v_div_scale_f32 v17, s[2:3], v16, v16, 2.0
	v_rcp_f32_e32 v18, v17
	s_nop 0
	v_fma_f32 v19, -v17, v18, 1.0
	v_fmac_f32_e32 v18, v19, v18
	v_div_scale_f32 v19, vcc, 2.0, v16, 2.0
	v_mul_f32_e32 v20, v19, v18
	v_fma_f32 v21, -v17, v20, v19
	v_fmac_f32_e32 v20, v21, v18
	v_fma_f32 v17, -v17, v20, v19
	v_div_fmas_f32 v17, v17, v18, v20
	v_div_fixup_f32 v16, v17, v16, 2.0
	v_sub_f32_e32 v16, 1.0, v16
	v_add_f32_e32 v16, 1.0, v16
	v_mul_f32_e32 v14, v14, v16
	v_mul_f32_e32 v16, 0x3d372713, v12
	v_mul_f32_e32 v16, v12, v16
	v_fma_f32 v16, v12, v16, v12
	v_mul_f32_e32 v16, 0x3f4c422a, v16
	v_add_f32_e32 v16, v16, v16
	v_mul_f32_e32 v16, 0x3fb8aa3b, v16
	v_exp_f32_e32 v16, v16
	v_mul_f32_e32 v12, 0.5, v12
	v_add_f32_e32 v16, 1.0, v16
	v_div_scale_f32 v17, s[2:3], v16, v16, 2.0
	v_rcp_f32_e32 v18, v17
	s_nop 0
	v_fma_f32 v19, -v17, v18, 1.0
	v_fmac_f32_e32 v18, v19, v18
	v_div_scale_f32 v19, vcc, 2.0, v16, 2.0
	v_mul_f32_e32 v20, v19, v18
	v_fma_f32 v21, -v17, v20, v19
	v_fmac_f32_e32 v20, v21, v18
	v_fma_f32 v17, -v17, v20, v19
	v_div_fmas_f32 v17, v17, v18, v20
	v_div_fixup_f32 v16, v17, v16, 2.0
	v_sub_f32_e32 v16, 1.0, v16
	v_add_f32_e32 v16, 1.0, v16
	v_mul_f32_e32 v16, v12, v16
	v_cvt_pk_bf16_f32 v12, v13, v15
	v_cvt_pk_bf16_f32 v13, v14, v16
	global_store_dwordx2 v[62:63], v[12:13], off offset:96
	v_mov_b32_e32 v12, v194
	v_mov_b32_e32 v13, v195
	v_mov_b32_e32 v14, v196
	v_mov_b32_e32 v15, v197
	v_add_f32_e32 v12, v8, v12
	v_add_f32_e32 v13, v9, v13
	v_mul_f32_e32 v9, 0x3d372713, v12
	v_mul_f32_e32 v9, v12, v9
	v_fma_f32 v9, v12, v9, v12
	v_mul_f32_e32 v9, 0x3f4c422a, v9
	v_add_f32_e32 v9, v9, v9
	v_mul_f32_e32 v9, 0x3fb8aa3b, v9
	v_exp_f32_e32 v9, v9
	v_add_f32_e32 v8, v11, v15
	v_add_f32_e32 v10, v10, v14
	v_add_f32_e32 v9, 1.0, v9
	v_div_scale_f32 v11, s[2:3], v9, v9, 2.0
	v_rcp_f32_e32 v14, v11
	s_nop 0
	v_fma_f32 v15, -v11, v14, 1.0
	v_fmac_f32_e32 v14, v15, v14
	v_div_scale_f32 v15, vcc, 2.0, v9, 2.0
	v_mul_f32_e32 v16, v15, v14
	v_fma_f32 v17, -v11, v16, v15
	v_fmac_f32_e32 v16, v17, v14
	v_fma_f32 v11, -v11, v16, v15
	v_div_fmas_f32 v11, v11, v14, v16
	v_div_fixup_f32 v9, v11, v9, 2.0
	v_sub_f32_e32 v9, 1.0, v9
	v_mul_f32_e32 v11, 0.5, v12
	v_add_f32_e32 v9, 1.0, v9
	v_mul_f32_e32 v9, v11, v9
	v_mul_f32_e32 v11, 0x3d372713, v13
	v_mul_f32_e32 v11, v13, v11
	v_fma_f32 v11, v13, v11, v13
	v_mul_f32_e32 v11, 0x3f4c422a, v11
	v_add_f32_e32 v11, v11, v11
	v_mul_f32_e32 v11, 0x3fb8aa3b, v11
; DEVI void store_bf4(bf16_t* p, f32x4 v) { u32x2 w; w.x = pk2(v[0], v[1]); w.y = pk2(v[2], v[3]); *(u32x2*)p = w; }
;   DEVI void operator()(int m, int n, f32x4 v, float) const {
;     const float4 bb = *(const float4*)(c1 + n);
;     float x[4] = {v[0] + bb.x, v[1] + bb.y, v[2] + bb.z, v[3] + bb.w};
;     f32x4 o;
; #pragma unroll
;     for (int j = 0; j < 4; ++j) {
;       float y = 0.7978845608028654f * (x[j] + 0.044715f * x[j] * x[j] * x[j]);
;       float th = 1.f - 2.f / (__expf(2.f * y) + 1.f);
;       o[j] = 0.5f * x[j] * (1.f + th);
;     }
;     store_bf4(hid + (size_t)m * 128 + n, o);
	v_exp_f32_e32 v11, v11
	s_nop 0
	v_add_f32_e32 v11, 1.0, v11
	v_div_scale_f32 v12, s[2:3], v11, v11, 2.0
	v_rcp_f32_e32 v14, v12
	s_nop 0
	v_fma_f32 v15, -v12, v14, 1.0
	v_fmac_f32_e32 v14, v15, v14
	v_div_scale_f32 v15, vcc, 2.0, v11, 2.0
	v_mul_f32_e32 v16, v15, v14
	v_fma_f32 v17, -v12, v16, v15
	v_fmac_f32_e32 v16, v17, v14
	v_fma_f32 v12, -v12, v16, v15
	v_div_fmas_f32 v12, v12, v14, v16
	v_div_fixup_f32 v11, v12, v11, 2.0
	v_sub_f32_e32 v11, 1.0, v11
	v_mul_f32_e32 v12, 0.5, v13
	v_add_f32_e32 v11, 1.0, v11
	v_mul_f32_e32 v11, v12, v11
	v_mul_f32_e32 v12, 0x3d372713, v10
	v_mul_f32_e32 v12, v10, v12
	v_fma_f32 v12, v10, v12, v10
	v_mul_f32_e32 v12, 0x3f4c422a, v12
	v_add_f32_e32 v12, v12, v12
	v_mul_f32_e32 v12, 0x3fb8aa3b, v12
	v_exp_f32_e32 v12, v12
	v_mul_f32_e32 v10, 0.5, v10
	v_add_f32_e32 v12, 1.0, v12
	v_div_scale_f32 v13, s[2:3], v12, v12, 2.0
	v_rcp_f32_e32 v14, v13
	s_nop 0
	v_fma_f32 v15, -v13, v14, 1.0
	v_fmac_f32_e32 v14, v15, v14
	v_div_scale_f32 v15, vcc, 2.0, v12, 2.0
	v_mul_f32_e32 v16, v15, v14
	v_fma_f32 v17, -v13, v16, v15
	v_fmac_f32_e32 v16, v17, v14
	v_fma_f32 v13, -v13, v16, v15
	v_div_fmas_f32 v13, v13, v14, v16
	v_div_fixup_f32 v12, v13, v12, 2.0
	v_sub_f32_e32 v12, 1.0, v12
	v_add_f32_e32 v12, 1.0, v12
	v_mul_f32_e32 v10, v10, v12
	v_mul_f32_e32 v12, 0x3d372713, v8
	v_mul_f32_e32 v12, v8, v12
	v_fma_f32 v12, v8, v12, v8
	v_mul_f32_e32 v12, 0x3f4c422a, v12
	v_add_f32_e32 v12, v12, v12
	v_mul_f32_e32 v12, 0x3fb8aa3b, v12
	v_exp_f32_e32 v12, v12
	v_mul_f32_e32 v8, 0.5, v8
	v_add_f32_e32 v12, 1.0, v12
	v_div_scale_f32 v13, s[2:3], v12, v12, 2.0
	v_rcp_f32_e32 v14, v13
	s_nop 0
	v_fma_f32 v15, -v13, v14, 1.0
	v_fmac_f32_e32 v14, v15, v14
	v_div_scale_f32 v15, vcc, 2.0, v12, 2.0
	v_mul_f32_e32 v16, v15, v14
	v_fma_f32 v17, -v13, v16, v15
	v_fmac_f32_e32 v16, v17, v14
	v_fma_f32 v13, -v13, v16, v15
	v_div_fmas_f32 v13, v13, v14, v16
	v_div_fixup_f32 v12, v13, v12, 2.0
	v_sub_f32_e32 v12, 1.0, v12
	v_add_f32_e32 v12, 1.0, v12
	v_mul_f32_e32 v12, v8, v12
	v_cvt_pk_bf16_f32 v8, v9, v11
	v_cvt_pk_bf16_f32 v9, v10, v12
	global_store_dwordx2 v[58:59], v[8:9], off offset:96
	v_mov_b32_e32 v8, v194
	v_mov_b32_e32 v9, v195
	v_mov_b32_e32 v10, v196
	v_mov_b32_e32 v11, v197
	v_add_f32_e32 v8, v4, v8
	v_add_f32_e32 v9, v5, v9
	v_mul_f32_e32 v5, 0x3d372713, v8
	v_mul_f32_e32 v5, v8, v5
	v_fma_f32 v5, v8, v5, v8
	v_mul_f32_e32 v5, 0x3f4c422a, v5
	v_add_f32_e32 v5, v5, v5
	v_mul_f32_e32 v5, 0x3fb8aa3b, v5
	v_exp_f32_e32 v5, v5
	v_add_f32_e32 v4, v7, v11
	v_add_f32_e32 v6, v6, v10
	v_add_f32_e32 v5, 1.0, v5
	v_div_scale_f32 v7, s[2:3], v5, v5, 2.0
	v_rcp_f32_e32 v10, v7
	s_nop 0
	v_fma_f32 v11, -v7, v10, 1.0
	v_fmac_f32_e32 v10, v11, v10
	v_div_scale_f32 v11, vcc, 2.0, v5, 2.0
	v_mul_f32_e32 v12, v11, v10
	v_fma_f32 v13, -v7, v12, v11
	v_fmac_f32_e32 v12, v13, v10
	v_fma_f32 v7, -v7, v12, v11
	v_div_fmas_f32 v7, v7, v10, v12
	v_div_fixup_f32 v5, v7, v5, 2.0
	v_sub_f32_e32 v5, 1.0, v5
	v_mul_f32_e32 v7, 0.5, v8
	v_add_f32_e32 v5, 1.0, v5
	v_mul_f32_e32 v5, v7, v5
	v_mul_f32_e32 v7, 0x3d372713, v9
	v_mul_f32_e32 v7, v9, v7
	v_fma_f32 v7, v9, v7, v9
	v_mul_f32_e32 v7, 0x3f4c422a, v7
	v_add_f32_e32 v7, v7, v7
	v_mul_f32_e32 v7, 0x3fb8aa3b, v7
	v_exp_f32_e32 v7, v7
	s_nop 0
	v_add_f32_e32 v7, 1.0, v7
	v_div_scale_f32 v8, s[2:3], v7, v7, 2.0
	v_rcp_f32_e32 v10, v8
	s_nop 0
	v_fma_f32 v11, -v8, v10, 1.0
	v_fmac_f32_e32 v10, v11, v10
	v_div_scale_f32 v11, vcc, 2.0, v7, 2.0
	v_mul_f32_e32 v12, v11, v10
	v_fma_f32 v13, -v8, v12, v11
	v_fmac_f32_e32 v12, v13, v10
	v_fma_f32 v8, -v8, v12, v11
	v_div_fmas_f32 v8, v8, v10, v12
	v_div_fixup_f32 v7, v8, v7, 2.0
	v_sub_f32_e32 v7, 1.0, v7
	v_mul_f32_e32 v8, 0.5, v9
	v_add_f32_e32 v7, 1.0, v7
	v_mul_f32_e32 v7, v8, v7
	v_mul_f32_e32 v8, 0x3d372713, v6
	v_mul_f32_e32 v8, v6, v8
	v_fma_f32 v8, v6, v8, v6
	v_mul_f32_e32 v8, 0x3f4c422a, v8
	v_add_f32_e32 v8, v8, v8
	v_mul_f32_e32 v8, 0x3fb8aa3b, v8
	v_exp_f32_e32 v8, v8
	v_mul_f32_e32 v6, 0.5, v6
	v_add_f32_e32 v8, 1.0, v8
	v_div_scale_f32 v9, s[2:3], v8, v8, 2.0
	v_rcp_f32_e32 v10, v9
	s_nop 0
	v_fma_f32 v11, -v9, v10, 1.0
	v_fmac_f32_e32 v10, v11, v10
	v_div_scale_f32 v11, vcc, 2.0, v8, 2.0
	v_mul_f32_e32 v12, v11, v10
	v_fma_f32 v13, -v9, v12, v11
	v_fmac_f32_e32 v12, v13, v10
	v_fma_f32 v9, -v9, v12, v11
	v_div_fmas_f32 v9, v9, v10, v12
	v_div_fixup_f32 v8, v9, v8, 2.0
	v_sub_f32_e32 v8, 1.0, v8
	v_add_f32_e32 v8, 1.0, v8
; DEVI void store_bf4(bf16_t* p, f32x4 v) { u32x2 w; w.x = pk2(v[0], v[1]); w.y = pk2(v[2], v[3]); *(u32x2*)p = w; }
; DEVI int opaque_tid(int wv) { int t; asm volatile("v_mbcnt_lo_u32_b32 %0, -1, 0\n\tv_mbcnt_hi_u32_b32 %0, -1, %0" : "=v"(t)); return wv * 64 + t; }
;   DEVI void operator()(int m, int n, f32x4 v, float) const {
;     const float4 bb = *(const float4*)(c1 + n);
;     float x[4] = {v[0] + bb.x, v[1] + bb.y, v[2] + bb.z, v[3] + bb.w};
;     f32x4 o;
; #pragma unroll
;     for (int j = 0; j < 4; ++j) {
;       float y = 0.7978845608028654f * (x[j] + 0.044715f * x[j] * x[j] * x[j]);
;       float th = 1.f - 2.f / (__expf(2.f * y) + 1.f);
;       o[j] = 0.5f * x[j] * (1.f + th);
;     }
;     store_bf4(hid + (size_t)m * 128 + n, o);
; DEVI int next_item(unsigned* ctr, int* slot, int wv) {
;   __syncthreads();
;   if (opaque_tid(wv) == 0) *slot = (int)atomicAdd(ctr, 1u);
;   __syncthreads();
	v_mul_f32_e32 v6, v6, v8
	v_mul_f32_e32 v8, 0x3d372713, v4
	v_mul_f32_e32 v8, v4, v8
	v_fma_f32 v8, v4, v8, v4
	v_mul_f32_e32 v8, 0x3f4c422a, v8
	v_add_f32_e32 v8, v8, v8
	v_mul_f32_e32 v8, 0x3fb8aa3b, v8
	v_exp_f32_e32 v8, v8
	v_mul_f32_e32 v4, 0.5, v4
	v_add_f32_e32 v8, 1.0, v8
	v_div_scale_f32 v9, s[2:3], v8, v8, 2.0
	v_rcp_f32_e32 v10, v9
	s_nop 0
	v_fma_f32 v11, -v9, v10, 1.0
	v_fmac_f32_e32 v10, v11, v10
	v_div_scale_f32 v11, vcc, 2.0, v8, 2.0
	v_mul_f32_e32 v12, v11, v10
	v_fma_f32 v13, -v9, v12, v11
	v_fmac_f32_e32 v12, v13, v10
	v_fma_f32 v9, -v9, v12, v11
	v_div_fmas_f32 v9, v9, v10, v12
	v_div_fixup_f32 v8, v9, v8, 2.0
	v_sub_f32_e32 v8, 1.0, v8
	v_add_f32_e32 v8, 1.0, v8
	v_mul_f32_e32 v8, v4, v8
	v_cvt_pk_bf16_f32 v4, v5, v7
	v_cvt_pk_bf16_f32 v5, v6, v8
	global_store_dwordx2 v[54:55], v[4:5], off offset:96
	v_mov_b32_e32 v4, v194
	v_mov_b32_e32 v5, v195
	v_mov_b32_e32 v6, v196
	v_mov_b32_e32 v7, v197
	v_add_f32_e32 v4, v0, v4
	v_add_f32_e32 v5, v1, v5
	v_mul_f32_e32 v1, 0x3d372713, v4
	v_mul_f32_e32 v1, v4, v1
	v_fma_f32 v1, v4, v1, v4
	v_mul_f32_e32 v1, 0x3f4c422a, v1
	v_add_f32_e32 v1, v1, v1
	v_mul_f32_e32 v1, 0x3fb8aa3b, v1
	v_exp_f32_e32 v1, v1
	v_add_f32_e32 v0, v3, v7
	v_add_f32_e32 v2, v2, v6
	v_add_f32_e32 v1, 1.0, v1
	v_div_scale_f32 v3, s[0:1], v1, v1, 2.0
	v_rcp_f32_e32 v6, v3
	s_nop 0
	v_fma_f32 v7, -v3, v6, 1.0
	v_fmac_f32_e32 v6, v7, v6
	v_div_scale_f32 v7, vcc, 2.0, v1, 2.0
	v_mul_f32_e32 v8, v7, v6
	v_fma_f32 v9, -v3, v8, v7
	v_fmac_f32_e32 v8, v9, v6
	v_fma_f32 v3, -v3, v8, v7
	v_div_fmas_f32 v3, v3, v6, v8
	v_div_fixup_f32 v1, v3, v1, 2.0
	v_sub_f32_e32 v1, 1.0, v1
	v_mul_f32_e32 v3, 0.5, v4
	v_add_f32_e32 v1, 1.0, v1
	v_mul_f32_e32 v1, v3, v1
	v_mul_f32_e32 v3, 0x3d372713, v5
	v_mul_f32_e32 v3, v5, v3
	v_fma_f32 v3, v5, v3, v5
	v_mul_f32_e32 v3, 0x3f4c422a, v3
	v_add_f32_e32 v3, v3, v3
	v_mul_f32_e32 v3, 0x3fb8aa3b, v3
	v_exp_f32_e32 v3, v3
	s_nop 0
	v_add_f32_e32 v3, 1.0, v3
	v_div_scale_f32 v4, s[0:1], v3, v3, 2.0
	v_rcp_f32_e32 v6, v4
	s_nop 0
	v_fma_f32 v7, -v4, v6, 1.0
	v_fmac_f32_e32 v6, v7, v6
	v_div_scale_f32 v7, vcc, 2.0, v3, 2.0
	v_mul_f32_e32 v8, v7, v6
	v_fma_f32 v9, -v4, v8, v7
	v_fmac_f32_e32 v8, v9, v6
	v_fma_f32 v4, -v4, v8, v7
	v_div_fmas_f32 v4, v4, v6, v8
	v_div_fixup_f32 v3, v4, v3, 2.0
	v_sub_f32_e32 v3, 1.0, v3
	v_mul_f32_e32 v4, 0.5, v5
	v_add_f32_e32 v3, 1.0, v3
	v_mul_f32_e32 v3, v4, v3
	v_mul_f32_e32 v4, 0x3d372713, v2
	v_mul_f32_e32 v4, v2, v4
	v_fma_f32 v4, v2, v4, v2
	v_mul_f32_e32 v4, 0x3f4c422a, v4
	v_add_f32_e32 v4, v4, v4
	v_mul_f32_e32 v4, 0x3fb8aa3b, v4
	v_exp_f32_e32 v4, v4
	v_mul_f32_e32 v2, 0.5, v2
	v_add_f32_e32 v4, 1.0, v4
	v_div_scale_f32 v5, s[0:1], v4, v4, 2.0
	v_rcp_f32_e32 v6, v5
	s_nop 0
	v_fma_f32 v7, -v5, v6, 1.0
	v_fmac_f32_e32 v6, v7, v6
	v_div_scale_f32 v7, vcc, 2.0, v4, 2.0
	v_mul_f32_e32 v8, v7, v6
	v_fma_f32 v9, -v5, v8, v7
	v_fmac_f32_e32 v8, v9, v6
	v_fma_f32 v5, -v5, v8, v7
	v_div_fmas_f32 v5, v5, v6, v8
	v_div_fixup_f32 v4, v5, v4, 2.0
	v_sub_f32_e32 v4, 1.0, v4
	v_add_f32_e32 v4, 1.0, v4
	v_mul_f32_e32 v2, v2, v4
	v_mul_f32_e32 v4, 0x3d372713, v0
	v_mul_f32_e32 v4, v0, v4
	v_fma_f32 v4, v0, v4, v0
	v_mul_f32_e32 v4, 0x3f4c422a, v4
	v_add_f32_e32 v4, v4, v4
	v_mul_f32_e32 v4, 0x3fb8aa3b, v4
	v_exp_f32_e32 v4, v4
	v_mul_f32_e32 v0, 0.5, v0
	v_add_f32_e32 v4, 1.0, v4
	v_div_scale_f32 v5, s[0:1], v4, v4, 2.0
	v_rcp_f32_e32 v6, v5
	v_readlane_b32 s0, v253, 48
	v_fma_f32 v7, -v5, v6, 1.0
	v_fmac_f32_e32 v6, v7, v6
	v_div_scale_f32 v7, vcc, 2.0, v4, 2.0
	v_mul_f32_e32 v8, v7, v6
	v_fma_f32 v9, -v5, v8, v7
	v_fmac_f32_e32 v8, v9, v6
	v_fma_f32 v5, -v5, v8, v7
	v_div_fmas_f32 v5, v5, v6, v8
	v_div_fixup_f32 v4, v5, v4, 2.0
	v_sub_f32_e32 v4, 1.0, v4
	v_add_f32_e32 v4, 1.0, v4
	v_mul_f32_e32 v4, v0, v4
	v_cvt_pk_bf16_f32 v0, v1, v3
	v_cvt_pk_bf16_f32 v1, v2, v4
	global_store_dwordx2 v[50:51], v[0:1], off offset:96
	s_barrier
	v_mbcnt_lo_u32_b32 v0, -1, 0
	v_mbcnt_hi_u32_b32 v0, -1, v0
	s_nop 0
	v_cmp_eq_u32_e32 vcc, s0, v0
	s_and_saveexec_b64 s[0:1], vcc
	s_movk_i32 s16, 0x1ff
	s_cbranch_execz .LBB0_838
	s_mov_b64 s[6:7], exec
	v_mbcnt_lo_u32_b32 v0, s6, 0
	v_mbcnt_hi_u32_b32 v0, s7, v0
	v_cmp_eq_u32_e32 vcc, 0, v0
	s_and_saveexec_b64 s[4:5], vcc
	s_cbranch_execz .LBB0_837
	s_bcnt1_i32_b64 s2, s[6:7]
	v_mov_b32_e32 v1, s2
	v_readlane_b32 s2, v255, 21
	v_readlane_b32 s3, v255, 22
	s_nop 4
	global_atomic_add v1, v33, v1, s[2:3] sc0
	s_branch .LBB0_837
